# MMA segments at s_setprio 1 but set before the barrier / cleared after it: no instruction between barrier and MFMAs, no mid-segment toggles
# speedup vs baseline: 1.0128x; 1.0014x over previous
; template <class Epi, class Sched, bool ALIGN_EPI = false, bool SP2 = false>
; __device__ __forceinline__ void gemm_phase(PG8_LAS unsigned char* lds, const Gemm g, const Sched& S, const Epi& E) {
;     ...
;         const bool has_next = S.next(ui + 1, nxt);
;         const char* nA = has_next ? (const char*)g.A + (size_t)nxt.pm * tstepA : cA; const char* nB = has_next ? (const char*)g.Bt + (size_t)nxt.pn * tstepB : cB;
;     ...
;         if constexpr (Epi::PEEL) {
;             const char* a1 = cA + kstepA; const char* a2 = cA + 2 * kstepA; const char* b2 = cB + 2 * kstepB; const char* a3 = a2 + kstepA; const char* b3 = b2 + kstepB;
;             PG8_ITER(8);
.LBB0_160:
	s_ashr_i32 s55, s54, 31
	s_lshl_b64 s[2:3], s[54:55], 15
	v_readlane_b32 s8, v255, 15
	s_add_u32 s12, s8, s2
	v_readlane_b32 s2, v255, 16
	s_addc_u32 s13, s2, s3
	s_ashr_i32 s49, s48, 31
	s_lshl_b64 s[2:3], s[48:49], 19
	v_readlane_b32 s8, v255, 29
	s_add_u32 s46, s8, s2
	v_readlane_b32 s2, v255, 40
	s_addc_u32 s47, s2, s3
	s_add_u32 s28, s24, 0x800000
	s_addc_u32 s29, s25, 0
	s_add_u32 s42, s24, 0xc00000
	s_addc_u32 s43, s25, 0
	s_add_i32 s55, 0, 0x10000
	s_and_b64 s[2:3], s[30:31], exec
	s_cselect_b32 s27, s13, s25
	s_cselect_b32 s44, s12, s24
	s_add_i32 vcc_hi, 0, 0x14000
	v_add_u32_e32 v142, s55, v97
	v_add_u32_e32 v143, vcc_hi, v97
	ds_read_b128 v[0:3], v142
	ds_read_b128 v[4:7], v142 offset:1024
	ds_read_b128 v[8:11], v142 offset:2048
	ds_read_b128 v[12:15], v142 offset:3072
	ds_read_b128 v[16:19], v143
	s_waitcnt lgkmcnt(0)
	ds_read_b128 v[20:23], v143 offset:1024
	ds_read_b128 v[24:27], v143 offset:2048
	ds_read_b128 v[28:31], v143 offset:3072
	v_writelane_b32 v255, s30, 33
	s_and_b64 s[2:3], s[30:31], exec
	s_cselect_b32 s45, s47, s1
	v_writelane_b32 v255, s31, 34
	s_cselect_b32 s49, s46, s0
	s_add_u32 s2, s24, 0x404000
	s_addc_u32 s3, s25, 0
	s_add_i32 s50, s22, 0xc000
	s_mov_b32 m0, s50
	s_add_i32 s51, s22, 0xe000
	ds_read_b128 v[32:35], v161
	ds_read_b128 v[36:39], v161 offset:1024
	ds_read_b128 v[40:43], v161 offset:2048
	ds_read_b128 v[44:47], v161 offset:3072
	ds_read_b128 v[48:51], v161 offset:4096
	ds_read_b128 v[52:55], v161 offset:5120
	ds_read_b128 v[56:59], v161 offset:6144
	ds_read_b128 v[60:63], v161 offset:7168
	global_load_lds_dwordx4 v130, s[2:3]
	s_mov_b32 m0, s51
	s_nop 0
	global_load_lds_dwordx4 v134, s[2:3]
	s_setprio 1
	s_waitcnt vmcnt(8)
	s_waitcnt lgkmcnt(0)
	s_barrier
	s_waitcnt lgkmcnt(0)
	v_mfma_f32_16x16x32_bf16 v[64:67], v[0:3], v[32:35], 0
	v_mfma_f32_16x16x32_bf16 v[68:71], v[8:11], v[32:35], 0
	v_mfma_f32_16x16x32_bf16 v[72:75], v[0:3], v[40:43], 0
	v_mfma_f32_16x16x32_bf16 v[76:79], v[8:11], v[40:43], 0
	v_mfma_f32_16x16x32_bf16 v[80:83], v[0:3], v[48:51], 0
	v_mfma_f32_16x16x32_bf16 v[84:87], v[8:11], v[48:51], 0
	v_mfma_f32_16x16x32_bf16 v[88:91], v[0:3], v[56:59], 0
	v_mfma_f32_16x16x32_bf16 v[92:95], v[8:11], v[56:59], 0
	v_mfma_f32_16x16x32_bf16 v[64:67], v[4:7], v[36:39], v[64:67]
	v_mfma_f32_16x16x32_bf16 v[68:71], v[12:15], v[36:39], v[68:71]
	v_mfma_f32_16x16x32_bf16 v[72:75], v[4:7], v[44:47], v[72:75]
	v_mfma_f32_16x16x32_bf16 v[76:79], v[12:15], v[44:47], v[76:79]
	v_mfma_f32_16x16x32_bf16 v[80:83], v[4:7], v[52:55], v[80:83]
	v_mfma_f32_16x16x32_bf16 v[84:87], v[12:15], v[52:55], v[84:87]
	v_mfma_f32_16x16x32_bf16 v[88:91], v[4:7], v[60:63], v[88:91]
	v_mfma_f32_16x16x32_bf16 v[98:101], v[12:15], v[60:63], v[92:95]
	v_mfma_f32_16x16x32_bf16 v[92:95], v[16:19], v[32:35], 0
	v_mfma_f32_16x16x32_bf16 v[32:35], v[24:27], v[32:35], 0
	v_mfma_f32_16x16x32_bf16 v[106:109], v[20:23], v[36:39], v[92:95]
	v_mfma_f32_16x16x32_bf16 v[32:35], v[28:31], v[36:39], v[32:35]
	v_mfma_f32_16x16x32_bf16 v[36:39], v[16:19], v[40:43], 0
	v_mfma_f32_16x16x32_bf16 v[40:43], v[24:27], v[40:43], 0
	v_mfma_f32_16x16x32_bf16 v[36:39], v[20:23], v[44:47], v[36:39]
	v_mfma_f32_16x16x32_bf16 v[40:43], v[28:31], v[44:47], v[40:43]
	v_mfma_f32_16x16x32_bf16 v[44:47], v[16:19], v[48:51], 0
	v_mfma_f32_16x16x32_bf16 v[48:51], v[24:27], v[48:51], 0
	v_mfma_f32_16x16x32_bf16 v[44:47], v[20:23], v[52:55], v[44:47]
	v_mfma_f32_16x16x32_bf16 v[48:51], v[28:31], v[52:55], v[48:51]
	v_mfma_f32_16x16x32_bf16 v[52:55], v[16:19], v[56:59], 0
	v_mfma_f32_16x16x32_bf16 v[56:59], v[24:27], v[56:59], 0
	v_mfma_f32_16x16x32_bf16 v[52:55], v[20:23], v[60:63], v[52:55]
	v_mfma_f32_16x16x32_bf16 v[56:59], v[28:31], v[60:63], v[56:59]
	s_barrier
	s_setprio 0
	v_lshl_add_u64 v[158:159], s[0:1], 0, v[132:133]
	s_mov_b64 s[2:3], 0x100
	s_add_i32 s55, s55, s10
	v_lshl_add_u64 v[144:145], v[158:159], 0, s[2:3]
	s_mov_b32 m0, s55
	v_lshl_add_u64 v[178:179], s[0:1], 0, v[136:137]
	s_add_i32 vcc_lo, s55, 0x2000
	ds_read_b128 v[60:63], v161 offset:16384
	ds_read_b128 v[92:95], v161 offset:17408
	ds_read_b128 v[102:105], v161 offset:18432
	ds_read_b128 v[110:113], v161 offset:19456
	ds_read_b128 v[114:117], v161 offset:20480
	ds_read_b128 v[118:121], v161 offset:21504
	ds_read_b128 v[122:125], v161 offset:22528
	ds_read_b128 v[126:129], v161 offset:23552
	global_load_lds_dwordx4 v[144:145], off
	v_lshl_add_u64 v[144:145], v[178:179], 0, s[2:3]
	s_add_u32 s2, s0, 0x40100
	s_mov_b32 m0, vcc_lo
	s_addc_u32 s3, s1, 0
	s_add_i32 vcc_hi, vcc_hi, s10
	global_load_lds_dwordx4 v[144:145], off
	s_mov_b32 m0, vcc_hi
	s_add_i32 s56, vcc_hi, 0x2000
	global_load_lds_dwordx4 v132, s[2:3]
	s_mov_b32 m0, s56
	s_nop 0
	global_load_lds_dwordx4 v136, s[2:3]
	s_mov_b32 m0, s22
	s_nop 0
	global_load_lds_dwordx4 v130, s[28:29]
	s_mov_b32 m0, s23
	s_nop 0
	global_load_lds_dwordx4 v134, s[28:29]
	s_setprio 1
	s_waitcnt vmcnt(8)
	s_waitcnt lgkmcnt(0)
	s_barrier
	s_waitcnt lgkmcnt(0)
	v_mfma_f32_16x16x32_bf16 v[144:147], v[0:3], v[60:63], 0
	v_mfma_f32_16x16x32_bf16 v[154:157], v[0:3], v[102:105], 0
	v_mfma_f32_16x16x32_bf16 v[166:169], v[0:3], v[114:117], 0
	v_mfma_f32_16x16x32_bf16 v[0:3], v[0:3], v[122:125], 0
	v_mfma_f32_16x16x32_bf16 v[146:149], v[4:7], v[92:95], v[144:147]
	v_mfma_f32_16x16x32_bf16 v[154:157], v[4:7], v[110:113], v[154:157]
	v_mfma_f32_16x16x32_bf16 v[166:169], v[4:7], v[118:121], v[166:169]
	v_mfma_f32_16x16x32_bf16 v[0:3], v[4:7], v[126:129], v[0:3]
	v_mfma_f32_16x16x32_bf16 v[4:7], v[8:11], v[122:125], 0
	v_mfma_f32_16x16x32_bf16 v[150:153], v[8:11], v[60:63], 0
	v_mfma_f32_16x16x32_bf16 v[162:165], v[8:11], v[102:105], 0
	v_mfma_f32_16x16x32_bf16 v[170:173], v[8:11], v[114:117], 0
	v_mfma_f32_16x16x32_bf16 v[4:7], v[12:15], v[126:129], v[4:7]
	v_mfma_f32_16x16x32_bf16 v[150:153], v[12:15], v[92:95], v[150:153]
	v_mfma_f32_16x16x32_bf16 v[162:165], v[12:15], v[110:113], v[162:165]
	v_mfma_f32_16x16x32_bf16 v[170:173], v[12:15], v[118:121], v[170:173]
	v_mfma_f32_16x16x32_bf16 v[12:15], v[24:27], v[60:63], 0
	v_mfma_f32_16x16x32_bf16 v[174:177], v[28:31], v[92:95], v[12:15]
	v_mfma_f32_16x16x32_bf16 v[12:15], v[16:19], v[102:105], 0
	v_mfma_f32_16x16x32_bf16 v[180:183], v[20:23], v[110:113], v[12:15]
	v_mfma_f32_16x16x32_bf16 v[12:15], v[24:27], v[102:105], 0
	v_mfma_f32_16x16x32_bf16 v[184:187], v[28:31], v[110:113], v[12:15]
	v_mfma_f32_16x16x32_bf16 v[12:15], v[16:19], v[114:117], 0
	v_mfma_f32_16x16x32_bf16 v[188:191], v[20:23], v[118:121], v[12:15]
	v_mfma_f32_16x16x32_bf16 v[12:15], v[24:27], v[114:117], 0
	v_mfma_f32_16x16x32_bf16 v[8:11], v[16:19], v[60:63], 0
	v_mfma_f32_16x16x32_bf16 v[192:195], v[28:31], v[118:121], v[12:15]
	v_mfma_f32_16x16x32_bf16 v[12:15], v[16:19], v[122:125], 0
	v_mfma_f32_16x16x32_bf16 v[8:11], v[20:23], v[92:95], v[8:11]
	v_mfma_f32_16x16x32_bf16 v[196:199], v[20:23], v[126:129], v[12:15]
	v_mfma_f32_16x16x32_bf16 v[12:15], v[24:27], v[122:125], 0
	v_mfma_f32_16x16x32_bf16 v[200:203], v[28:31], v[126:129], v[12:15]
	s_barrier
	s_setprio 0
	s_add_i32 s30, 0, 0x18000
	s_add_i32 s57, 0, 0x1c000
	v_add_u32_e32 v144, s30, v97
	v_add_u32_e32 v145, s57, v97
	s_nop 0
	ds_read_b128 v[12:15], v144
	ds_read_b128 v[16:19], v144 offset:1024
	ds_read_b128 v[24:27], v144 offset:2048
	ds_read_b128 v[204:207], v144 offset:3072
	ds_read_b128 v[208:211], v145
	ds_read_b128 v[212:215], v145 offset:1024
	ds_read_b128 v[216:219], v145 offset:2048
	ds_read_b128 v[220:223], v145 offset:3072
	s_add_u32 s2, s24, 0x804000
	s_addc_u32 s3, s25, 0
	s_mov_b32 m0, s39
	ds_read_b128 v[20:23], v161 offset:32768
	ds_read_b128 v[28:31], v161 offset:33792
	ds_read_b128 v[60:63], v161 offset:34816
	ds_read_b128 v[224:227], v161 offset:35840
	ds_read_b128 v[228:231], v161 offset:36864
	ds_read_b128 v[234:237], v161 offset:37888
	ds_read_b128 v[238:241], v161 offset:38912
	ds_read_b128 v[242:245], v161 offset:39936
	global_load_lds_dwordx4 v130, s[2:3]
	s_mov_b32 m0, s52
	s_nop 0
	global_load_lds_dwordx4 v134, s[2:3]
	s_setprio 1
	s_waitcnt vmcnt(8)
	s_waitcnt lgkmcnt(0)
	s_barrier
	s_waitcnt lgkmcnt(0)
	v_mfma_f32_16x16x32_bf16 v[64:67], v[12:15], v[20:23], v[64:67]
	v_mfma_f32_16x16x32_bf16 v[126:129], v[16:19], v[28:31], v[64:67]
	v_mfma_f32_16x16x32_bf16 v[64:67], v[24:27], v[20:23], v[68:71]
	v_mfma_f32_16x16x32_bf16 v[118:121], v[204:207], v[28:31], v[64:67]
	v_mfma_f32_16x16x32_bf16 v[64:67], v[12:15], v[60:63], v[72:75]
	v_mfma_f32_16x16x32_bf16 v[110:113], v[16:19], v[224:227], v[64:67]
	v_mfma_f32_16x16x32_bf16 v[64:67], v[24:27], v[60:63], v[76:79]
	v_mfma_f32_16x16x32_bf16 v[102:105], v[204:207], v[224:227], v[64:67]
	v_mfma_f32_16x16x32_bf16 v[64:67], v[12:15], v[228:231], v[80:83]
	v_mfma_f32_16x16x32_bf16 v[92:95], v[16:19], v[234:237], v[64:67]
	v_mfma_f32_16x16x32_bf16 v[64:67], v[24:27], v[228:231], v[84:87]
	v_mfma_f32_16x16x32_bf16 v[84:87], v[204:207], v[234:237], v[64:67]
	v_mfma_f32_16x16x32_bf16 v[64:67], v[12:15], v[238:241], v[88:91]
	v_mfma_f32_16x16x32_bf16 v[76:79], v[16:19], v[242:245], v[64:67]
	v_mfma_f32_16x16x32_bf16 v[64:67], v[24:27], v[238:241], v[98:101]
	v_mfma_f32_16x16x32_bf16 v[68:71], v[204:207], v[242:245], v[64:67]
	v_mfma_f32_16x16x32_bf16 v[64:67], v[208:211], v[20:23], v[106:109]
	v_mfma_f32_16x16x32_bf16 v[20:23], v[216:219], v[20:23], v[32:35]
	v_mfma_f32_16x16x32_bf16 v[114:117], v[220:223], v[28:31], v[20:23]
	v_mfma_f32_16x16x32_bf16 v[20:23], v[208:211], v[60:63], v[36:39]
	v_mfma_f32_16x16x32_bf16 v[106:109], v[212:215], v[224:227], v[20:23]
	v_mfma_f32_16x16x32_bf16 v[20:23], v[216:219], v[60:63], v[40:43]
	v_mfma_f32_16x16x32_bf16 v[98:101], v[220:223], v[224:227], v[20:23]
	v_mfma_f32_16x16x32_bf16 v[20:23], v[208:211], v[228:231], v[44:47]
	v_mfma_f32_16x16x32_bf16 v[88:91], v[212:215], v[234:237], v[20:23]
	v_mfma_f32_16x16x32_bf16 v[20:23], v[216:219], v[228:231], v[48:51]
	v_mfma_f32_16x16x32_bf16 v[80:83], v[220:223], v[234:237], v[20:23]
	v_mfma_f32_16x16x32_bf16 v[20:23], v[208:211], v[238:241], v[52:55]
	v_mfma_f32_16x16x32_bf16 v[72:75], v[212:215], v[242:245], v[20:23]
	v_mfma_f32_16x16x32_bf16 v[20:23], v[216:219], v[238:241], v[56:59]
	v_mfma_f32_16x16x32_bf16 v[122:125], v[212:215], v[28:31], v[64:67]
	v_mfma_f32_16x16x32_bf16 v[64:67], v[220:223], v[242:245], v[20:23]
	s_barrier
; template <class Epi, class Sched, bool ALIGN_EPI = false, bool SP2 = false>
; __device__ __forceinline__ void gemm_phase(PG8_LAS unsigned char* lds, const Gemm g, const Sched& S, const Epi& E) {
;     ...
;         if constexpr (Epi::PEEL) {
;             const char* a1 = cA + kstepA; const char* a2 = cA + 2 * kstepA; const char* b2 = cB + 2 * kstepB; const char* a3 = a2 + kstepA; const char* b3 = b2 + kstepB;
;             PG8_ITER(8);
;         }
;         for (int t = (Epi::PEEL ? 2 : 0); t < nt; t += 2) {
;             const bool last = (t == nt - 2);
;             const char* a1 = cA + (size_t)(t + 1) * kstepA;
;             const char* a2 = last ? nA : cA + (size_t)(t + 2) * kstepA; const char* b2 = last ? nB : cB + (size_t)(t + 2) * kstepB;
;             const char* a3 = a2 + kstepA; const char* b3 = b2 + kstepB;
;             PG8_ITER(8);
	s_setprio 0
	s_mov_b64 s[2:3], 0x180
	s_add_i32 s30, s30, s10
	s_nop 1
	v_lshl_add_u64 v[20:21], v[158:159], 0, s[2:3]
	s_mov_b32 m0, s30
	s_add_i32 s31, s30, 0x2000
	ds_read_b128 v[32:35], v161 offset:49152
	ds_read_b128 v[40:43], v161 offset:50176
	ds_read_b128 v[224:227], v161 offset:51200
	ds_read_b128 v[228:231], v161 offset:52224
	ds_read_b128 v[234:237], v161 offset:53248
	ds_read_b128 v[238:241], v161 offset:54272
	ds_read_b128 v[242:245], v161 offset:55296
	ds_read_b128 v[246:249], v161 offset:56320
	global_load_lds_dwordx4 v[20:21], off
	v_lshl_add_u64 v[20:21], v[178:179], 0, s[2:3]
	s_add_u32 s2, s0, 0x40180
	s_mov_b32 m0, s31
	s_addc_u32 s3, s1, 0
	s_add_i32 s57, s57, s10
	global_load_lds_dwordx4 v[20:21], off
	s_mov_b32 m0, s57
	s_add_i32 s96, s57, 0x2000
	global_load_lds_dwordx4 v132, s[2:3]
	s_mov_b32 m0, s96
	s_nop 0
	global_load_lds_dwordx4 v136, s[2:3]
	s_mov_b32 m0, s11
	s_nop 0
	global_load_lds_dwordx4 v130, s[42:43]
	s_mov_b32 m0, s19
	s_nop 0
	global_load_lds_dwordx4 v134, s[42:43]
	s_setprio 1
	s_waitcnt vmcnt(8)
	s_waitcnt lgkmcnt(0)
	s_barrier
	s_waitcnt lgkmcnt(0)
	v_mfma_f32_16x16x32_bf16 v[20:23], v[12:15], v[32:35], v[146:149]
	v_mfma_f32_16x16x32_bf16 v[60:63], v[16:19], v[40:43], v[20:23]
	v_mfma_f32_16x16x32_bf16 v[20:23], v[24:27], v[32:35], v[150:153]
	v_mfma_f32_16x16x32_bf16 v[52:55], v[204:207], v[40:43], v[20:23]
	v_mfma_f32_16x16x32_bf16 v[20:23], v[12:15], v[224:227], v[154:157]
	v_mfma_f32_16x16x32_bf16 v[44:47], v[16:19], v[228:231], v[20:23]
	v_mfma_f32_16x16x32_bf16 v[20:23], v[24:27], v[224:227], v[162:165]
	v_mfma_f32_16x16x32_bf16 v[36:39], v[204:207], v[228:231], v[20:23]
	v_mfma_f32_16x16x32_bf16 v[20:23], v[12:15], v[234:237], v[166:169]
	v_mfma_f32_16x16x32_bf16 v[0:3], v[12:15], v[242:245], v[0:3]
	v_mfma_f32_16x16x32_bf16 v[28:31], v[16:19], v[238:241], v[20:23]
	v_mfma_f32_16x16x32_bf16 v[20:23], v[24:27], v[234:237], v[170:173]
	v_mfma_f32_16x16x32_bf16 v[12:15], v[16:19], v[246:249], v[0:3]
	v_mfma_f32_16x16x32_bf16 v[0:3], v[24:27], v[242:245], v[4:7]
	v_mfma_f32_16x16x32_bf16 v[20:23], v[204:207], v[238:241], v[20:23]
	v_mfma_f32_16x16x32_bf16 v[4:7], v[204:207], v[246:249], v[0:3]
	v_mfma_f32_16x16x32_bf16 v[0:3], v[208:211], v[32:35], v[8:11]
	v_mfma_f32_16x16x32_bf16 v[56:59], v[212:215], v[40:43], v[0:3]
	v_mfma_f32_16x16x32_bf16 v[0:3], v[216:219], v[32:35], v[174:177]
	v_mfma_f32_16x16x32_bf16 v[48:51], v[220:223], v[40:43], v[0:3]
	v_mfma_f32_16x16x32_bf16 v[0:3], v[208:211], v[224:227], v[180:183]
	v_mfma_f32_16x16x32_bf16 v[40:43], v[212:215], v[228:231], v[0:3]
	v_mfma_f32_16x16x32_bf16 v[0:3], v[216:219], v[224:227], v[184:187]
	v_mfma_f32_16x16x32_bf16 v[32:35], v[220:223], v[228:231], v[0:3]
	v_mfma_f32_16x16x32_bf16 v[0:3], v[208:211], v[234:237], v[188:191]
	v_mfma_f32_16x16x32_bf16 v[24:27], v[212:215], v[238:241], v[0:3]
	v_mfma_f32_16x16x32_bf16 v[0:3], v[216:219], v[234:237], v[192:195]
	v_mfma_f32_16x16x32_bf16 v[16:19], v[220:223], v[238:241], v[0:3]
	v_mfma_f32_16x16x32_bf16 v[0:3], v[208:211], v[242:245], v[196:199]
	v_mfma_f32_16x16x32_bf16 v[8:11], v[212:215], v[246:249], v[0:3]
	v_mfma_f32_16x16x32_bf16 v[0:3], v[216:219], v[242:245], v[200:203]
	v_mfma_f32_16x16x32_bf16 v[0:3], v[220:223], v[246:249], v[0:3]
	s_barrier
	s_setprio 0
	s_add_u32 s3, s0, 0x200
	s_addc_u32 s2, s1, 0
	s_add_u32 s0, s24, 0xc04000
	s_addc_u32 s1, s25, 0
	s_mov_b32 s18, 0
.LBB0_161:
	ds_read_b128 v[146:149], v142
	ds_read_b128 v[150:153], v142 offset:1024
	ds_read_b128 v[154:157], v142 offset:2048
	ds_read_b128 v[162:165], v142 offset:3072
	ds_read_b128 v[166:169], v143
	ds_read_b128 v[170:173], v143 offset:1024
	ds_read_b128 v[174:177], v143 offset:2048
	ds_read_b128 v[180:183], v143 offset:3072
	s_add_u32 s8, s0, 0x3fc000
	s_addc_u32 s9, s1, 0
	s_cmp_eq_u32 s18, 12
	s_cselect_b32 s28, s44, s8
	s_cselect_b32 s29, s27, s9
	s_cselect_b32 s42, s49, s3
	s_cselect_b32 s43, s45, s2
	s_add_u32 s24, s28, 0x400000
	s_addc_u32 s25, s29, 0
	s_mov_b32 m0, s50
	ds_read_b128 v[184:187], v161
	ds_read_b128 v[188:191], v161 offset:1024
	ds_read_b128 v[192:195], v161 offset:2048
	ds_read_b128 v[196:199], v161 offset:3072
	ds_read_b128 v[200:203], v161 offset:4096
	ds_read_b128 v[204:207], v161 offset:5120
	ds_read_b128 v[208:211], v161 offset:6144
	ds_read_b128 v[212:215], v161 offset:7168
	global_load_lds_dwordx4 v140, s[0:1]
	s_mov_b32 m0, s51
	s_nop 0
	global_load_lds_dwordx4 v138, s[0:1]
	s_setprio 1
	s_waitcnt vmcnt(8)
	s_waitcnt lgkmcnt(0)
	s_barrier
	s_waitcnt lgkmcnt(0)
	v_mfma_f32_16x16x32_bf16 v[126:129], v[146:149], v[184:187], v[126:129]
	v_mfma_f32_16x16x32_bf16 v[118:121], v[154:157], v[184:187], v[118:121]
	v_mfma_f32_16x16x32_bf16 v[102:105], v[154:157], v[192:195], v[102:105]
	v_mfma_f32_16x16x32_bf16 v[110:113], v[146:149], v[192:195], v[110:113]
	v_mfma_f32_16x16x32_bf16 v[92:95], v[146:149], v[200:203], v[92:95]
	v_mfma_f32_16x16x32_bf16 v[84:87], v[154:157], v[200:203], v[84:87]
	v_mfma_f32_16x16x32_bf16 v[68:71], v[154:157], v[208:211], v[68:71]
	v_mfma_f32_16x16x32_bf16 v[76:79], v[146:149], v[208:211], v[76:79]
	v_mfma_f32_16x16x32_bf16 v[126:129], v[150:153], v[188:191], v[126:129]
	v_mfma_f32_16x16x32_bf16 v[118:121], v[162:165], v[188:191], v[118:121]
	v_mfma_f32_16x16x32_bf16 v[102:105], v[162:165], v[196:199], v[102:105]
	v_mfma_f32_16x16x32_bf16 v[110:113], v[150:153], v[196:199], v[110:113]
	v_mfma_f32_16x16x32_bf16 v[92:95], v[150:153], v[204:207], v[92:95]
	v_mfma_f32_16x16x32_bf16 v[84:87], v[162:165], v[204:207], v[84:87]
	v_mfma_f32_16x16x32_bf16 v[68:71], v[162:165], v[212:215], v[68:71]
	v_mfma_f32_16x16x32_bf16 v[76:79], v[150:153], v[212:215], v[76:79]
	v_mfma_f32_16x16x32_bf16 v[122:125], v[166:169], v[184:187], v[122:125]
	v_mfma_f32_16x16x32_bf16 v[114:117], v[174:177], v[184:187], v[114:117]
	v_mfma_f32_16x16x32_bf16 v[98:101], v[174:177], v[192:195], v[98:101]
	v_mfma_f32_16x16x32_bf16 v[106:109], v[166:169], v[192:195], v[106:109]
	v_mfma_f32_16x16x32_bf16 v[88:91], v[166:169], v[200:203], v[88:91]
	v_mfma_f32_16x16x32_bf16 v[80:83], v[174:177], v[200:203], v[80:83]
	v_mfma_f32_16x16x32_bf16 v[64:67], v[174:177], v[208:211], v[64:67]
	v_mfma_f32_16x16x32_bf16 v[72:75], v[166:169], v[208:211], v[72:75]
	v_mfma_f32_16x16x32_bf16 v[122:125], v[170:173], v[188:191], v[122:125]
	v_mfma_f32_16x16x32_bf16 v[114:117], v[180:183], v[188:191], v[114:117]
	v_mfma_f32_16x16x32_bf16 v[98:101], v[180:183], v[196:199], v[98:101]
	v_mfma_f32_16x16x32_bf16 v[106:109], v[170:173], v[196:199], v[106:109]
	v_mfma_f32_16x16x32_bf16 v[88:91], v[170:173], v[204:207], v[88:91]
	v_mfma_f32_16x16x32_bf16 v[80:83], v[180:183], v[204:207], v[80:83]
	v_mfma_f32_16x16x32_bf16 v[64:67], v[180:183], v[212:215], v[64:67]
	v_mfma_f32_16x16x32_bf16 v[72:75], v[170:173], v[212:215], v[72:75]
	s_barrier
	s_setprio 0
	s_mov_b32 m0, s55
	s_add_u32 s8, s42, 0x40000
	ds_read_b128 v[184:187], v161 offset:16384
	ds_read_b128 v[188:191], v161 offset:17408
	ds_read_b128 v[192:195], v161 offset:18432
	ds_read_b128 v[196:199], v161 offset:19456
	ds_read_b128 v[200:203], v161 offset:20480
	ds_read_b128 v[204:207], v161 offset:21504
	ds_read_b128 v[208:211], v161 offset:22528
	ds_read_b128 v[212:215], v161 offset:23552
	global_load_lds_dwordx4 v132, s[42:43]
	s_mov_b32 m0, vcc_lo
	s_addc_u32 s9, s43, 0
	global_load_lds_dwordx4 v136, s[42:43]
	s_mov_b32 m0, vcc_hi
	s_nop 0
	global_load_lds_dwordx4 v132, s[8:9]
	s_mov_b32 m0, s56
	s_nop 0
	global_load_lds_dwordx4 v136, s[8:9]
	s_mov_b32 m0, s22
	s_nop 0
	global_load_lds_dwordx4 v130, s[28:29]
	s_mov_b32 m0, s23
	s_nop 0
	global_load_lds_dwordx4 v134, s[28:29]
	s_setprio 1
	s_waitcnt vmcnt(8)
	s_waitcnt lgkmcnt(0)
	s_barrier
	s_waitcnt lgkmcnt(0)
	v_mfma_f32_16x16x32_bf16 v[60:63], v[146:149], v[184:187], v[60:63]
	v_mfma_f32_16x16x32_bf16 v[52:55], v[154:157], v[184:187], v[52:55]
	v_mfma_f32_16x16x32_bf16 v[36:39], v[154:157], v[192:195], v[36:39]
	v_mfma_f32_16x16x32_bf16 v[44:47], v[146:149], v[192:195], v[44:47]
	v_mfma_f32_16x16x32_bf16 v[28:31], v[146:149], v[200:203], v[28:31]
	v_mfma_f32_16x16x32_bf16 v[20:23], v[154:157], v[200:203], v[20:23]
	v_mfma_f32_16x16x32_bf16 v[4:7], v[154:157], v[208:211], v[4:7]
	v_mfma_f32_16x16x32_bf16 v[12:15], v[146:149], v[208:211], v[12:15]
	v_mfma_f32_16x16x32_bf16 v[60:63], v[150:153], v[188:191], v[60:63]
	v_mfma_f32_16x16x32_bf16 v[52:55], v[162:165], v[188:191], v[52:55]
	v_mfma_f32_16x16x32_bf16 v[36:39], v[162:165], v[196:199], v[36:39]
	v_mfma_f32_16x16x32_bf16 v[44:47], v[150:153], v[196:199], v[44:47]
	v_mfma_f32_16x16x32_bf16 v[28:31], v[150:153], v[204:207], v[28:31]
	v_mfma_f32_16x16x32_bf16 v[20:23], v[162:165], v[204:207], v[20:23]
	v_mfma_f32_16x16x32_bf16 v[4:7], v[162:165], v[212:215], v[4:7]
	v_mfma_f32_16x16x32_bf16 v[12:15], v[150:153], v[212:215], v[12:15]
	v_mfma_f32_16x16x32_bf16 v[56:59], v[166:169], v[184:187], v[56:59]
	v_mfma_f32_16x16x32_bf16 v[48:51], v[174:177], v[184:187], v[48:51]
	v_mfma_f32_16x16x32_bf16 v[32:35], v[174:177], v[192:195], v[32:35]
	v_mfma_f32_16x16x32_bf16 v[40:43], v[166:169], v[192:195], v[40:43]
	v_mfma_f32_16x16x32_bf16 v[24:27], v[166:169], v[200:203], v[24:27]
	v_mfma_f32_16x16x32_bf16 v[16:19], v[174:177], v[200:203], v[16:19]
	v_mfma_f32_16x16x32_bf16 v[0:3], v[174:177], v[208:211], v[0:3]
	v_mfma_f32_16x16x32_bf16 v[8:11], v[166:169], v[208:211], v[8:11]
	v_mfma_f32_16x16x32_bf16 v[56:59], v[170:173], v[188:191], v[56:59]
	v_mfma_f32_16x16x32_bf16 v[48:51], v[180:183], v[188:191], v[48:51]
	v_mfma_f32_16x16x32_bf16 v[32:35], v[180:183], v[196:199], v[32:35]
	v_mfma_f32_16x16x32_bf16 v[40:43], v[170:173], v[196:199], v[40:43]
	v_mfma_f32_16x16x32_bf16 v[24:27], v[170:173], v[204:207], v[24:27]
	v_mfma_f32_16x16x32_bf16 v[16:19], v[180:183], v[204:207], v[16:19]
	v_mfma_f32_16x16x32_bf16 v[0:3], v[180:183], v[212:215], v[0:3]
	v_mfma_f32_16x16x32_bf16 v[8:11], v[170:173], v[212:215], v[8:11]
	s_barrier
	s_setprio 0
	ds_read_b128 v[146:149], v144
	ds_read_b128 v[150:153], v144 offset:1024
	ds_read_b128 v[154:157], v144 offset:2048
	ds_read_b128 v[162:165], v144 offset:3072
	ds_read_b128 v[166:169], v145
	ds_read_b128 v[170:173], v145 offset:1024
	ds_read_b128 v[174:177], v145 offset:2048
	ds_read_b128 v[180:183], v145 offset:3072
	s_add_u32 s8, s28, 0x4000
	s_addc_u32 s9, s29, 0
	s_mov_b32 m0, s39
	ds_read_b128 v[184:187], v161 offset:32768
	ds_read_b128 v[188:191], v161 offset:33792
	ds_read_b128 v[192:195], v161 offset:34816
	ds_read_b128 v[196:199], v161 offset:35840
	ds_read_b128 v[200:203], v161 offset:36864
	ds_read_b128 v[204:207], v161 offset:37888
	ds_read_b128 v[208:211], v161 offset:38912
	ds_read_b128 v[212:215], v161 offset:39936
	global_load_lds_dwordx4 v130, s[8:9]
	s_mov_b32 m0, s52
	s_nop 0
	global_load_lds_dwordx4 v134, s[8:9]
	s_setprio 1
	s_waitcnt vmcnt(8)
	s_waitcnt lgkmcnt(0)
	s_barrier
; #define PG8_BAR __builtin_amdgcn_s_barrier()
; template <class Epi, class Sched, bool ALIGN_EPI = false, bool SP2 = false>
; __device__ __forceinline__ void gemm_phase(PG8_LAS unsigned char* lds, const Gemm g, const Sched& S, const Epi& E) {
;     ...
;             PG8_ITER(8);
;         }
;     ...
;         if constexpr (ALIGN_EPI) { if (wr == 0) PG8_BAR; }
	s_waitcnt lgkmcnt(0)
	v_mfma_f32_16x16x32_bf16 v[126:129], v[146:149], v[184:187], v[126:129]
	v_mfma_f32_16x16x32_bf16 v[118:121], v[154:157], v[184:187], v[118:121]
	v_mfma_f32_16x16x32_bf16 v[102:105], v[154:157], v[192:195], v[102:105]
	v_mfma_f32_16x16x32_bf16 v[110:113], v[146:149], v[192:195], v[110:113]
	v_mfma_f32_16x16x32_bf16 v[92:95], v[146:149], v[200:203], v[92:95]
	v_mfma_f32_16x16x32_bf16 v[84:87], v[154:157], v[200:203], v[84:87]
	v_mfma_f32_16x16x32_bf16 v[68:71], v[154:157], v[208:211], v[68:71]
	v_mfma_f32_16x16x32_bf16 v[76:79], v[146:149], v[208:211], v[76:79]
	v_mfma_f32_16x16x32_bf16 v[126:129], v[150:153], v[188:191], v[126:129]
	v_mfma_f32_16x16x32_bf16 v[118:121], v[162:165], v[188:191], v[118:121]
	v_mfma_f32_16x16x32_bf16 v[102:105], v[162:165], v[196:199], v[102:105]
	v_mfma_f32_16x16x32_bf16 v[110:113], v[150:153], v[196:199], v[110:113]
	v_mfma_f32_16x16x32_bf16 v[92:95], v[150:153], v[204:207], v[92:95]
	v_mfma_f32_16x16x32_bf16 v[84:87], v[162:165], v[204:207], v[84:87]
	v_mfma_f32_16x16x32_bf16 v[68:71], v[162:165], v[212:215], v[68:71]
	v_mfma_f32_16x16x32_bf16 v[76:79], v[150:153], v[212:215], v[76:79]
	v_mfma_f32_16x16x32_bf16 v[122:125], v[166:169], v[184:187], v[122:125]
	v_mfma_f32_16x16x32_bf16 v[114:117], v[174:177], v[184:187], v[114:117]
	v_mfma_f32_16x16x32_bf16 v[98:101], v[174:177], v[192:195], v[98:101]
	v_mfma_f32_16x16x32_bf16 v[106:109], v[166:169], v[192:195], v[106:109]
	v_mfma_f32_16x16x32_bf16 v[88:91], v[166:169], v[200:203], v[88:91]
	v_mfma_f32_16x16x32_bf16 v[80:83], v[174:177], v[200:203], v[80:83]
	v_mfma_f32_16x16x32_bf16 v[64:67], v[174:177], v[208:211], v[64:67]
	v_mfma_f32_16x16x32_bf16 v[72:75], v[166:169], v[208:211], v[72:75]
	v_mfma_f32_16x16x32_bf16 v[122:125], v[170:173], v[188:191], v[122:125]
	v_mfma_f32_16x16x32_bf16 v[114:117], v[180:183], v[188:191], v[114:117]
	v_mfma_f32_16x16x32_bf16 v[98:101], v[180:183], v[196:199], v[98:101]
	v_mfma_f32_16x16x32_bf16 v[106:109], v[170:173], v[196:199], v[106:109]
	v_mfma_f32_16x16x32_bf16 v[88:91], v[170:173], v[204:207], v[88:91]
	v_mfma_f32_16x16x32_bf16 v[80:83], v[180:183], v[204:207], v[80:83]
	v_mfma_f32_16x16x32_bf16 v[64:67], v[180:183], v[212:215], v[64:67]
	v_mfma_f32_16x16x32_bf16 v[72:75], v[170:173], v[212:215], v[72:75]
	s_barrier
	s_setprio 0
	s_mov_b32 m0, s30
	s_add_u32 s100, s42, 0x80
	s_addc_u32 s101, s43, 0
	s_add_u32 s8, s42, 0x40080
	ds_read_b128 v[184:187], v161 offset:49152
	ds_read_b128 v[188:191], v161 offset:50176
	ds_read_b128 v[192:195], v161 offset:51200
	ds_read_b128 v[196:199], v161 offset:52224
	ds_read_b128 v[200:203], v161 offset:53248
	ds_read_b128 v[204:207], v161 offset:54272
	ds_read_b128 v[208:211], v161 offset:55296
	ds_read_b128 v[212:215], v161 offset:56320
	global_load_lds_dwordx4 v132, s[100:101]
	s_mov_b32 m0, s31
	s_addc_u32 s9, s43, 0
	global_load_lds_dwordx4 v136, s[100:101]
	s_mov_b32 m0, s57
	s_nop 0
	global_load_lds_dwordx4 v132, s[8:9]
	s_mov_b32 m0, s96
	s_nop 0
	global_load_lds_dwordx4 v136, s[8:9]
	s_mov_b32 m0, s11
	s_nop 0
	global_load_lds_dwordx4 v130, s[24:25]
	s_mov_b32 m0, s19
	s_nop 0
	global_load_lds_dwordx4 v134, s[24:25]
	s_setprio 1
	s_waitcnt vmcnt(8)
	s_waitcnt lgkmcnt(0)
	s_barrier
	s_waitcnt lgkmcnt(0)
	v_mfma_f32_16x16x32_bf16 v[60:63], v[146:149], v[184:187], v[60:63]
	v_mfma_f32_16x16x32_bf16 v[52:55], v[154:157], v[184:187], v[52:55]
	v_mfma_f32_16x16x32_bf16 v[36:39], v[154:157], v[192:195], v[36:39]
	v_mfma_f32_16x16x32_bf16 v[44:47], v[146:149], v[192:195], v[44:47]
	v_mfma_f32_16x16x32_bf16 v[28:31], v[146:149], v[200:203], v[28:31]
	v_mfma_f32_16x16x32_bf16 v[20:23], v[154:157], v[200:203], v[20:23]
	v_mfma_f32_16x16x32_bf16 v[4:7], v[154:157], v[208:211], v[4:7]
	v_mfma_f32_16x16x32_bf16 v[12:15], v[146:149], v[208:211], v[12:15]
	v_mfma_f32_16x16x32_bf16 v[60:63], v[150:153], v[188:191], v[60:63]
	v_mfma_f32_16x16x32_bf16 v[52:55], v[162:165], v[188:191], v[52:55]
	v_mfma_f32_16x16x32_bf16 v[36:39], v[162:165], v[196:199], v[36:39]
	v_mfma_f32_16x16x32_bf16 v[44:47], v[150:153], v[196:199], v[44:47]
	v_mfma_f32_16x16x32_bf16 v[28:31], v[150:153], v[204:207], v[28:31]
	v_mfma_f32_16x16x32_bf16 v[20:23], v[162:165], v[204:207], v[20:23]
	v_mfma_f32_16x16x32_bf16 v[4:7], v[162:165], v[212:215], v[4:7]
	v_mfma_f32_16x16x32_bf16 v[12:15], v[150:153], v[212:215], v[12:15]
	v_mfma_f32_16x16x32_bf16 v[56:59], v[166:169], v[184:187], v[56:59]
	v_mfma_f32_16x16x32_bf16 v[48:51], v[174:177], v[184:187], v[48:51]
	v_mfma_f32_16x16x32_bf16 v[32:35], v[174:177], v[192:195], v[32:35]
	v_mfma_f32_16x16x32_bf16 v[40:43], v[166:169], v[192:195], v[40:43]
	v_mfma_f32_16x16x32_bf16 v[24:27], v[166:169], v[200:203], v[24:27]
	v_mfma_f32_16x16x32_bf16 v[16:19], v[174:177], v[200:203], v[16:19]
	v_mfma_f32_16x16x32_bf16 v[0:3], v[174:177], v[208:211], v[0:3]
	v_mfma_f32_16x16x32_bf16 v[8:11], v[166:169], v[208:211], v[8:11]
	v_mfma_f32_16x16x32_bf16 v[56:59], v[170:173], v[188:191], v[56:59]
	v_mfma_f32_16x16x32_bf16 v[48:51], v[180:183], v[188:191], v[48:51]
	v_mfma_f32_16x16x32_bf16 v[32:35], v[180:183], v[196:199], v[32:35]
	v_mfma_f32_16x16x32_bf16 v[40:43], v[170:173], v[196:199], v[40:43]
	v_mfma_f32_16x16x32_bf16 v[24:27], v[170:173], v[204:207], v[24:27]
	v_mfma_f32_16x16x32_bf16 v[16:19], v[180:183], v[204:207], v[16:19]
	v_mfma_f32_16x16x32_bf16 v[0:3], v[180:183], v[212:215], v[0:3]
	v_mfma_f32_16x16x32_bf16 v[8:11], v[170:173], v[212:215], v[8:11]
	s_barrier
	s_setprio 0
	s_add_i32 s18, s18, 2
	s_add_u32 s3, s3, 0x100
	s_addc_u32 s2, s2, 0
	s_add_u32 s0, s0, 0x800000
	s_addc_u32 s1, s1, 0
	s_cmp_gt_u32 s18, 13
	s_cbranch_scc0 .LBB0_161
	v_readlane_b32 s0, v255, 45
	v_readlane_b32 s1, v255, 46
	s_and_b64 vcc, exec, s[0:1]
	s_cbranch_vccz .LBB0_164
	s_barrier

; template <class Epi, class Sched, bool ALIGN_EPI = false, bool SP2 = false>
; __device__ __forceinline__ void gemm_phase(PG8_LAS unsigned char* lds, const Gemm g, const Sched& S, const Epi& E) {
;     ...
;         const bool has_next = S.next(ui + 1, nxt);
;         const char* nA = has_next ? (const char*)g.A + (size_t)nxt.pm * tstepA : cA; const char* nB = has_next ? (const char*)g.Bt + (size_t)nxt.pn * tstepB : cB;
;     ...
;         if constexpr (Epi::PEEL) {
;             const char* a1 = cA + kstepA; const char* a2 = cA + 2 * kstepA; const char* b2 = cB + 2 * kstepB; const char* a3 = a2 + kstepA; const char* b3 = b2 + kstepB;
;             PG8_ITER(8);
.LBB0_249:
	s_ashr_i32 s49, s48, 31
	s_lshl_b64 s[2:3], s[48:49], 15
	v_readlane_b32 s11, v255, 15
	s_add_u32 s50, s11, s2
	v_readlane_b32 s2, v255, 16
	s_addc_u32 s51, s2, s3
	s_ashr_i32 s47, s46, 31
	s_lshl_b64 s[2:3], s[46:47], 19
	s_add_u32 s52, s38, s2
	s_addc_u32 s53, s19, s3
	s_add_u32 s28, s42, 0x800000
	s_addc_u32 s29, s43, 0
	s_add_u32 s44, s42, 0xc00000
	s_addc_u32 s45, s43, 0
	s_add_i32 s99, 0, 0x10000
	s_and_b64 s[2:3], s[40:41], exec
	s_cselect_b32 s27, s51, s43
	s_cselect_b32 s47, s50, s42
	s_add_i32 vcc_hi, 0, 0x14000
	v_add_u32_e32 v130, s99, v97
	v_add_u32_e32 v131, vcc_hi, v97
	ds_read_b128 v[0:3], v130
	ds_read_b128 v[4:7], v130 offset:1024
	ds_read_b128 v[8:11], v130 offset:2048
	ds_read_b128 v[12:15], v130 offset:3072
	ds_read_b128 v[16:19], v131
	s_waitcnt lgkmcnt(0)
	ds_read_b128 v[20:23], v131 offset:1024
	ds_read_b128 v[24:27], v131 offset:2048
	ds_read_b128 v[28:31], v131 offset:3072
	s_and_b64 s[2:3], s[40:41], exec
	s_cselect_b32 s49, s53, s25
	s_cselect_b32 s54, s52, s24
	s_add_u32 s2, s42, 0x404000
	s_addc_u32 s3, s43, 0
	s_add_i32 s55, s22, 0xc000
	s_mov_b32 m0, s55
	s_add_i32 s98, s22, 0xe000
	ds_read_b128 v[32:35], v151
	ds_read_b128 v[36:39], v151 offset:1024
	ds_read_b128 v[40:43], v151 offset:2048
	ds_read_b128 v[44:47], v151 offset:3072
	ds_read_b128 v[48:51], v151 offset:4096
	ds_read_b128 v[52:55], v151 offset:5120
	ds_read_b128 v[56:59], v151 offset:6144
	ds_read_b128 v[60:63], v151 offset:7168
	global_load_lds_dwordx4 v134, s[2:3]
	s_mov_b32 m0, s98
	s_nop 0
	global_load_lds_dwordx4 v138, s[2:3]
	s_setprio 1
	s_waitcnt vmcnt(8)
	s_waitcnt lgkmcnt(0)
	s_barrier
	s_waitcnt lgkmcnt(0)
	v_mfma_f32_16x16x32_bf16 v[84:87], v[8:11], v[48:51], 0
	v_mfma_f32_16x16x32_bf16 v[88:91], v[12:15], v[52:55], v[84:87]
	v_mfma_f32_16x16x32_bf16 v[84:87], v[0:3], v[56:59], 0
	v_mfma_f32_16x16x32_bf16 v[64:67], v[0:3], v[32:35], 0
	v_mfma_f32_16x16x32_bf16 v[68:71], v[8:11], v[32:35], 0
	v_mfma_f32_16x16x32_bf16 v[72:75], v[0:3], v[40:43], 0
	v_mfma_f32_16x16x32_bf16 v[76:79], v[8:11], v[40:43], 0
	v_mfma_f32_16x16x32_bf16 v[80:83], v[0:3], v[48:51], 0
	v_mfma_f32_16x16x32_bf16 v[92:95], v[4:7], v[60:63], v[84:87]
	v_mfma_f32_16x16x32_bf16 v[84:87], v[8:11], v[56:59], 0
	v_mfma_f32_16x16x32_bf16 v[64:67], v[4:7], v[36:39], v[64:67]
	v_mfma_f32_16x16x32_bf16 v[68:71], v[12:15], v[36:39], v[68:71]
	v_mfma_f32_16x16x32_bf16 v[72:75], v[4:7], v[44:47], v[72:75]
	v_mfma_f32_16x16x32_bf16 v[76:79], v[12:15], v[44:47], v[76:79]
	v_mfma_f32_16x16x32_bf16 v[80:83], v[4:7], v[52:55], v[80:83]
	v_mfma_f32_16x16x32_bf16 v[106:109], v[12:15], v[60:63], v[84:87]
	v_mfma_f32_16x16x32_bf16 v[84:87], v[16:19], v[32:35], 0
	v_mfma_f32_16x16x32_bf16 v[32:35], v[24:27], v[32:35], 0
	v_mfma_f32_16x16x32_bf16 v[110:113], v[20:23], v[36:39], v[84:87]
	v_mfma_f32_16x16x32_bf16 v[32:35], v[28:31], v[36:39], v[32:35]
	v_mfma_f32_16x16x32_bf16 v[36:39], v[16:19], v[40:43], 0
	v_mfma_f32_16x16x32_bf16 v[40:43], v[24:27], v[40:43], 0
	v_mfma_f32_16x16x32_bf16 v[36:39], v[20:23], v[44:47], v[36:39]
	v_mfma_f32_16x16x32_bf16 v[40:43], v[28:31], v[44:47], v[40:43]
	v_mfma_f32_16x16x32_bf16 v[44:47], v[16:19], v[48:51], 0
	v_mfma_f32_16x16x32_bf16 v[48:51], v[24:27], v[48:51], 0
	v_mfma_f32_16x16x32_bf16 v[44:47], v[20:23], v[52:55], v[44:47]
	v_mfma_f32_16x16x32_bf16 v[48:51], v[28:31], v[52:55], v[48:51]
	v_mfma_f32_16x16x32_bf16 v[52:55], v[16:19], v[56:59], 0
	v_mfma_f32_16x16x32_bf16 v[56:59], v[24:27], v[56:59], 0
	v_mfma_f32_16x16x32_bf16 v[52:55], v[20:23], v[60:63], v[52:55]
	v_mfma_f32_16x16x32_bf16 v[56:59], v[28:31], v[60:63], v[56:59]
	s_barrier
	s_setprio 0
	v_lshl_add_u64 v[176:177], s[24:25], 0, v[136:137]
	s_mov_b64 s[2:3], 0x100
	s_add_i32 s99, s99, s10
	v_lshl_add_u64 v[132:133], v[176:177], 0, s[2:3]
	s_mov_b32 m0, s99
	v_lshl_add_u64 v[178:179], s[24:25], 0, v[140:141]
	s_add_i32 vcc_lo, s99, 0x2000
	ds_read_b128 v[60:63], v151 offset:16384
	ds_read_b128 v[84:87], v151 offset:17408
	ds_read_b128 v[98:101], v151 offset:18432
	ds_read_b128 v[102:105], v151 offset:19456
	ds_read_b128 v[114:117], v151 offset:20480
	ds_read_b128 v[118:121], v151 offset:21504
	ds_read_b128 v[122:125], v151 offset:22528
	ds_read_b128 v[126:129], v151 offset:23552
	global_load_lds_dwordx4 v[132:133], off
	v_lshl_add_u64 v[132:133], v[178:179], 0, s[2:3]
	s_add_u32 s2, s24, 0x40100
	s_mov_b32 m0, vcc_lo
	s_addc_u32 s3, s25, 0
	s_add_i32 vcc_hi, vcc_hi, s10
	global_load_lds_dwordx4 v[132:133], off
	s_mov_b32 m0, vcc_hi
	s_add_i32 s30, vcc_hi, 0x2000
	global_load_lds_dwordx4 v136, s[2:3]
	s_mov_b32 m0, s30
	s_mov_b64 s[34:35], 0x100
	global_load_lds_dwordx4 v140, s[2:3]
	s_mov_b32 m0, s22
	s_nop 0
	global_load_lds_dwordx4 v134, s[28:29]
	s_mov_b32 m0, s23
	s_nop 0
	global_load_lds_dwordx4 v138, s[28:29]
	s_setprio 1
	s_waitcnt vmcnt(8)
	s_waitcnt lgkmcnt(0)
	s_barrier
	s_waitcnt lgkmcnt(0)
	v_mfma_f32_16x16x32_bf16 v[146:149], v[0:3], v[60:63], 0
	v_mfma_f32_16x16x32_bf16 v[156:159], v[0:3], v[98:101], 0
	v_mfma_f32_16x16x32_bf16 v[164:167], v[0:3], v[114:117], 0
	v_mfma_f32_16x16x32_bf16 v[0:3], v[0:3], v[122:125], 0
	v_mfma_f32_16x16x32_bf16 v[146:149], v[4:7], v[84:87], v[146:149]
	v_mfma_f32_16x16x32_bf16 v[156:159], v[4:7], v[102:105], v[156:159]
	v_mfma_f32_16x16x32_bf16 v[164:167], v[4:7], v[118:121], v[164:167]
	v_mfma_f32_16x16x32_bf16 v[0:3], v[4:7], v[126:129], v[0:3]
	v_mfma_f32_16x16x32_bf16 v[4:7], v[8:11], v[122:125], 0
	v_mfma_f32_16x16x32_bf16 v[152:155], v[8:11], v[60:63], 0
	v_mfma_f32_16x16x32_bf16 v[160:163], v[8:11], v[98:101], 0
	v_mfma_f32_16x16x32_bf16 v[168:171], v[8:11], v[114:117], 0
	v_mfma_f32_16x16x32_bf16 v[8:11], v[12:15], v[126:129], v[4:7]
	v_mfma_f32_16x16x32_bf16 v[152:155], v[12:15], v[84:87], v[152:155]
	v_mfma_f32_16x16x32_bf16 v[160:163], v[12:15], v[102:105], v[160:163]
	v_mfma_f32_16x16x32_bf16 v[168:171], v[12:15], v[118:121], v[168:171]
	v_mfma_f32_16x16x32_bf16 v[4:7], v[16:19], v[60:63], 0
	v_mfma_f32_16x16x32_bf16 v[12:15], v[20:23], v[84:87], v[4:7]
	v_mfma_f32_16x16x32_bf16 v[4:7], v[24:27], v[60:63], 0
	v_mfma_f32_16x16x32_bf16 v[172:175], v[28:31], v[84:87], v[4:7]
	v_mfma_f32_16x16x32_bf16 v[4:7], v[16:19], v[98:101], 0
	v_mfma_f32_16x16x32_bf16 v[180:183], v[20:23], v[102:105], v[4:7]
	v_mfma_f32_16x16x32_bf16 v[4:7], v[24:27], v[98:101], 0
	v_mfma_f32_16x16x32_bf16 v[184:187], v[28:31], v[102:105], v[4:7]
	v_mfma_f32_16x16x32_bf16 v[4:7], v[16:19], v[114:117], 0
	v_mfma_f32_16x16x32_bf16 v[188:191], v[20:23], v[118:121], v[4:7]
	v_mfma_f32_16x16x32_bf16 v[4:7], v[24:27], v[114:117], 0
	v_mfma_f32_16x16x32_bf16 v[192:195], v[28:31], v[118:121], v[4:7]
	v_mfma_f32_16x16x32_bf16 v[4:7], v[16:19], v[122:125], 0
	v_mfma_f32_16x16x32_bf16 v[196:199], v[20:23], v[126:129], v[4:7]
	v_mfma_f32_16x16x32_bf16 v[4:7], v[24:27], v[122:125], 0
	v_mfma_f32_16x16x32_bf16 v[200:203], v[28:31], v[126:129], v[4:7]
	s_barrier
	s_setprio 0
	s_add_i32 s31, 0, 0x18000
	s_add_i32 s13, 0, 0x1c000
	v_add_u32_e32 v132, s31, v97
	v_add_u32_e32 v133, s13, v97
	s_nop 0
	ds_read_b128 v[4:7], v132
	ds_read_b128 v[24:27], v132 offset:1024
	ds_read_b128 v[28:31], v132 offset:2048
	ds_read_b128 v[60:63], v132 offset:3072
	ds_read_b128 v[204:207], v133
	ds_read_b128 v[208:211], v133 offset:1024
	ds_read_b128 v[212:215], v133 offset:2048
	ds_read_b128 v[216:219], v133 offset:3072
	s_add_u32 s2, s42, 0x804000
	s_addc_u32 s3, s43, 0
	s_mov_b32 m0, s39
	ds_read_b128 v[16:19], v151 offset:32768
	ds_read_b128 v[20:23], v151 offset:33792
	ds_read_b128 v[220:223], v151 offset:34816
	ds_read_b128 v[224:227], v151 offset:35840
	ds_read_b128 v[228:231], v151 offset:36864
	ds_read_b128 v[234:237], v151 offset:37888
	ds_read_b128 v[238:241], v151 offset:38912
	ds_read_b128 v[242:245], v151 offset:39936
	global_load_lds_dwordx4 v134, s[2:3]
	s_mov_b32 m0, s56
	s_nop 0
	global_load_lds_dwordx4 v138, s[2:3]
	s_setprio 1
	s_waitcnt vmcnt(8)
	s_waitcnt lgkmcnt(0)
	s_barrier
	s_waitcnt lgkmcnt(0)
	v_mfma_f32_16x16x32_bf16 v[64:67], v[4:7], v[16:19], v[64:67]
	v_mfma_f32_16x16x32_bf16 v[118:121], v[24:27], v[20:23], v[64:67]
	v_mfma_f32_16x16x32_bf16 v[64:67], v[28:31], v[16:19], v[68:71]
	v_mfma_f32_16x16x32_bf16 v[114:117], v[60:63], v[20:23], v[64:67]
	v_mfma_f32_16x16x32_bf16 v[64:67], v[4:7], v[220:223], v[72:75]
	v_mfma_f32_16x16x32_bf16 v[102:105], v[24:27], v[224:227], v[64:67]
	v_mfma_f32_16x16x32_bf16 v[64:67], v[28:31], v[220:223], v[76:79]
	v_mfma_f32_16x16x32_bf16 v[98:101], v[60:63], v[224:227], v[64:67]
	v_mfma_f32_16x16x32_bf16 v[64:67], v[4:7], v[228:231], v[80:83]
	v_mfma_f32_16x16x32_bf16 v[84:87], v[24:27], v[234:237], v[64:67]
	v_mfma_f32_16x16x32_bf16 v[64:67], v[28:31], v[228:231], v[88:91]
	v_mfma_f32_16x16x32_bf16 v[80:83], v[60:63], v[234:237], v[64:67]
	v_mfma_f32_16x16x32_bf16 v[64:67], v[4:7], v[238:241], v[92:95]
	v_mfma_f32_16x16x32_bf16 v[68:71], v[24:27], v[242:245], v[64:67]
	v_mfma_f32_16x16x32_bf16 v[64:67], v[28:31], v[238:241], v[106:109]
	v_mfma_f32_16x16x32_bf16 v[64:67], v[60:63], v[242:245], v[64:67]
	v_mfma_f32_16x16x32_bf16 v[72:75], v[204:207], v[16:19], v[110:113]
	v_mfma_f32_16x16x32_bf16 v[16:19], v[212:215], v[16:19], v[32:35]
	v_mfma_f32_16x16x32_bf16 v[122:125], v[216:219], v[20:23], v[16:19]
	v_mfma_f32_16x16x32_bf16 v[16:19], v[204:207], v[220:223], v[36:39]
	v_mfma_f32_16x16x32_bf16 v[110:113], v[208:211], v[224:227], v[16:19]
	v_mfma_f32_16x16x32_bf16 v[16:19], v[212:215], v[220:223], v[40:43]
	v_mfma_f32_16x16x32_bf16 v[106:109], v[216:219], v[224:227], v[16:19]
	v_mfma_f32_16x16x32_bf16 v[16:19], v[204:207], v[228:231], v[44:47]
	v_mfma_f32_16x16x32_bf16 v[92:95], v[208:211], v[234:237], v[16:19]
	v_mfma_f32_16x16x32_bf16 v[16:19], v[212:215], v[228:231], v[48:51]
	v_mfma_f32_16x16x32_bf16 v[88:91], v[216:219], v[234:237], v[16:19]
	v_mfma_f32_16x16x32_bf16 v[16:19], v[204:207], v[238:241], v[52:55]
	v_mfma_f32_16x16x32_bf16 v[76:79], v[208:211], v[242:245], v[16:19]
	v_mfma_f32_16x16x32_bf16 v[16:19], v[212:215], v[238:241], v[56:59]
	v_mfma_f32_16x16x32_bf16 v[126:129], v[208:211], v[20:23], v[72:75]
	v_mfma_f32_16x16x32_bf16 v[72:75], v[216:219], v[242:245], v[16:19]
	s_barrier
; template <class Epi, class Sched, bool ALIGN_EPI = false, bool SP2 = false>
; __device__ __forceinline__ void gemm_phase(PG8_LAS unsigned char* lds, const Gemm g, const Sched& S, const Epi& E) {
;     ...
;         for (int t = (Epi::PEEL ? 2 : 0); t < nt; t += 2) {
;             const bool last = (t == nt - 2);
;             const char* a1 = cA + (size_t)(t + 1) * kstepA;
;             const char* a2 = last ? nA : cA + (size_t)(t + 2) * kstepA; const char* b2 = last ? nB : cB + (size_t)(t + 2) * kstepB;
;             const char* a3 = a2 + kstepA; const char* b3 = b2 + kstepB;
;             PG8_ITER(8);
	s_setprio 0
	s_mov_b64 s[2:3], 0x180
	s_add_i32 s31, s31, s10
	s_nop 1
	v_lshl_add_u64 v[16:17], v[176:177], 0, s[2:3]
	s_mov_b32 m0, s31
	s_add_i32 s12, s31, 0x2000
	ds_read_b128 v[40:43], v151 offset:49152
	ds_read_b128 v[44:47], v151 offset:50176
	ds_read_b128 v[220:223], v151 offset:51200
	ds_read_b128 v[224:227], v151 offset:52224
	ds_read_b128 v[228:231], v151 offset:53248
	ds_read_b128 v[234:237], v151 offset:54272
	ds_read_b128 v[238:241], v151 offset:55296
	ds_read_b128 v[242:245], v151 offset:56320
	global_load_lds_dwordx4 v[16:17], off
	v_lshl_add_u64 v[16:17], v[178:179], 0, s[2:3]
	s_add_u32 s2, s24, 0x40180
	s_mov_b32 m0, s12
	s_addc_u32 s3, s25, 0
	s_add_i32 s13, s13, s10
	global_load_lds_dwordx4 v[16:17], off
	s_mov_b32 m0, s13
	s_add_i32 s11, s13, 0x2000
	global_load_lds_dwordx4 v136, s[2:3]
	s_mov_b32 m0, s11
	s_nop 0
	global_load_lds_dwordx4 v140, s[2:3]
	s_mov_b32 m0, s59
	s_nop 0
	global_load_lds_dwordx4 v134, s[44:45]
	s_mov_b32 m0, s96
	s_nop 0
	global_load_lds_dwordx4 v138, s[44:45]
	s_setprio 1
	s_waitcnt vmcnt(8)
	s_waitcnt lgkmcnt(0)
	s_barrier
	s_waitcnt lgkmcnt(0)
	v_mfma_f32_16x16x32_bf16 v[16:19], v[4:7], v[40:43], v[146:149]
	v_mfma_f32_16x16x32_bf16 v[52:55], v[24:27], v[44:47], v[16:19]
	v_mfma_f32_16x16x32_bf16 v[16:19], v[28:31], v[40:43], v[152:155]
	v_mfma_f32_16x16x32_bf16 v[48:51], v[60:63], v[44:47], v[16:19]
	v_mfma_f32_16x16x32_bf16 v[16:19], v[4:7], v[220:223], v[156:159]
	v_mfma_f32_16x16x32_bf16 v[36:39], v[24:27], v[224:227], v[16:19]
	v_mfma_f32_16x16x32_bf16 v[16:19], v[28:31], v[220:223], v[160:163]
	v_mfma_f32_16x16x32_bf16 v[32:35], v[60:63], v[224:227], v[16:19]
	v_mfma_f32_16x16x32_bf16 v[16:19], v[4:7], v[228:231], v[164:167]
	v_mfma_f32_16x16x32_bf16 v[0:3], v[4:7], v[238:241], v[0:3]
	v_mfma_f32_16x16x32_bf16 v[20:23], v[24:27], v[234:237], v[16:19]
	v_mfma_f32_16x16x32_bf16 v[16:19], v[28:31], v[228:231], v[168:171]
	v_mfma_f32_16x16x32_bf16 v[4:7], v[24:27], v[242:245], v[0:3]
	v_mfma_f32_16x16x32_bf16 v[0:3], v[28:31], v[238:241], v[8:11]
	v_mfma_f32_16x16x32_bf16 v[16:19], v[60:63], v[234:237], v[16:19]
	v_mfma_f32_16x16x32_bf16 v[0:3], v[60:63], v[242:245], v[0:3]
	v_mfma_f32_16x16x32_bf16 v[8:11], v[204:207], v[40:43], v[12:15]
	v_mfma_f32_16x16x32_bf16 v[60:63], v[208:211], v[44:47], v[8:11]
	v_mfma_f32_16x16x32_bf16 v[8:11], v[212:215], v[40:43], v[172:175]
	v_mfma_f32_16x16x32_bf16 v[56:59], v[216:219], v[44:47], v[8:11]
	v_mfma_f32_16x16x32_bf16 v[8:11], v[204:207], v[220:223], v[180:183]
	v_mfma_f32_16x16x32_bf16 v[44:47], v[208:211], v[224:227], v[8:11]
	v_mfma_f32_16x16x32_bf16 v[8:11], v[212:215], v[220:223], v[184:187]
	v_mfma_f32_16x16x32_bf16 v[40:43], v[216:219], v[224:227], v[8:11]
	v_mfma_f32_16x16x32_bf16 v[8:11], v[204:207], v[228:231], v[188:191]
	v_mfma_f32_16x16x32_bf16 v[28:31], v[208:211], v[234:237], v[8:11]
	v_mfma_f32_16x16x32_bf16 v[8:11], v[212:215], v[228:231], v[192:195]
	v_mfma_f32_16x16x32_bf16 v[24:27], v[216:219], v[234:237], v[8:11]
	v_mfma_f32_16x16x32_bf16 v[8:11], v[204:207], v[238:241], v[196:199]
	v_mfma_f32_16x16x32_bf16 v[12:15], v[208:211], v[242:245], v[8:11]
	v_mfma_f32_16x16x32_bf16 v[8:11], v[212:215], v[238:241], v[200:203]
	v_mfma_f32_16x16x32_bf16 v[8:11], v[216:219], v[242:245], v[8:11]
	s_barrier
	s_setprio 0
	s_add_u32 s3, s24, 0x200
	s_addc_u32 s2, s25, 0
	s_add_u32 s24, s42, 0xc04000
	s_addc_u32 s25, s43, 0
	s_mov_b32 s18, 0
.LBB0_250:
	ds_read_b128 v[146:149], v130
	ds_read_b128 v[152:155], v130 offset:1024
	ds_read_b128 v[156:159], v130 offset:2048
	ds_read_b128 v[160:163], v130 offset:3072
	ds_read_b128 v[164:167], v131
	ds_read_b128 v[168:171], v131 offset:1024
	ds_read_b128 v[172:175], v131 offset:2048
	ds_read_b128 v[180:183], v131 offset:3072
	s_add_u32 s16, s24, 0x3fc000
	s_addc_u32 s17, s25, 0
	s_cmp_eq_u32 s18, 12
	s_cselect_b32 s28, s47, s16
	s_cselect_b32 s29, s27, s17
	s_cselect_b32 s44, s54, s3
	s_cselect_b32 s45, s49, s2
	s_add_u32 s42, s28, 0x400000
	s_addc_u32 s43, s29, 0
	s_mov_b32 m0, s55
	ds_read_b128 v[184:187], v151
	ds_read_b128 v[188:191], v151 offset:1024
	ds_read_b128 v[192:195], v151 offset:2048
	ds_read_b128 v[196:199], v151 offset:3072
	ds_read_b128 v[200:203], v151 offset:4096
	ds_read_b128 v[204:207], v151 offset:5120
	ds_read_b128 v[208:211], v151 offset:6144
	ds_read_b128 v[212:215], v151 offset:7168
	global_load_lds_dwordx4 v144, s[24:25]
	s_mov_b32 m0, s98
	s_nop 0
	global_load_lds_dwordx4 v142, s[24:25]
	s_setprio 1
	s_waitcnt vmcnt(8)
	s_waitcnt lgkmcnt(0)
	s_barrier
	s_waitcnt lgkmcnt(0)
	v_mfma_f32_16x16x32_bf16 v[118:121], v[146:149], v[184:187], v[118:121]
	v_mfma_f32_16x16x32_bf16 v[114:117], v[156:159], v[184:187], v[114:117]
	v_mfma_f32_16x16x32_bf16 v[98:101], v[156:159], v[192:195], v[98:101]
	v_mfma_f32_16x16x32_bf16 v[102:105], v[146:149], v[192:195], v[102:105]
	v_mfma_f32_16x16x32_bf16 v[84:87], v[146:149], v[200:203], v[84:87]
	v_mfma_f32_16x16x32_bf16 v[80:83], v[156:159], v[200:203], v[80:83]
	v_mfma_f32_16x16x32_bf16 v[64:67], v[156:159], v[208:211], v[64:67]
	v_mfma_f32_16x16x32_bf16 v[68:71], v[146:149], v[208:211], v[68:71]
	v_mfma_f32_16x16x32_bf16 v[118:121], v[152:155], v[188:191], v[118:121]
	v_mfma_f32_16x16x32_bf16 v[114:117], v[160:163], v[188:191], v[114:117]
	v_mfma_f32_16x16x32_bf16 v[98:101], v[160:163], v[196:199], v[98:101]
	v_mfma_f32_16x16x32_bf16 v[102:105], v[152:155], v[196:199], v[102:105]
	v_mfma_f32_16x16x32_bf16 v[84:87], v[152:155], v[204:207], v[84:87]
	v_mfma_f32_16x16x32_bf16 v[80:83], v[160:163], v[204:207], v[80:83]
	v_mfma_f32_16x16x32_bf16 v[64:67], v[160:163], v[212:215], v[64:67]
	v_mfma_f32_16x16x32_bf16 v[68:71], v[152:155], v[212:215], v[68:71]
	v_mfma_f32_16x16x32_bf16 v[126:129], v[164:167], v[184:187], v[126:129]
	v_mfma_f32_16x16x32_bf16 v[122:125], v[172:175], v[184:187], v[122:125]
	v_mfma_f32_16x16x32_bf16 v[106:109], v[172:175], v[192:195], v[106:109]
	v_mfma_f32_16x16x32_bf16 v[110:113], v[164:167], v[192:195], v[110:113]
	v_mfma_f32_16x16x32_bf16 v[92:95], v[164:167], v[200:203], v[92:95]
	v_mfma_f32_16x16x32_bf16 v[88:91], v[172:175], v[200:203], v[88:91]
	v_mfma_f32_16x16x32_bf16 v[72:75], v[172:175], v[208:211], v[72:75]
	v_mfma_f32_16x16x32_bf16 v[76:79], v[164:167], v[208:211], v[76:79]
	v_mfma_f32_16x16x32_bf16 v[126:129], v[168:171], v[188:191], v[126:129]
	v_mfma_f32_16x16x32_bf16 v[122:125], v[180:183], v[188:191], v[122:125]
	v_mfma_f32_16x16x32_bf16 v[106:109], v[180:183], v[196:199], v[106:109]
	v_mfma_f32_16x16x32_bf16 v[110:113], v[168:171], v[196:199], v[110:113]
	v_mfma_f32_16x16x32_bf16 v[92:95], v[168:171], v[204:207], v[92:95]
	v_mfma_f32_16x16x32_bf16 v[88:91], v[180:183], v[204:207], v[88:91]
	v_mfma_f32_16x16x32_bf16 v[72:75], v[180:183], v[212:215], v[72:75]
	v_mfma_f32_16x16x32_bf16 v[76:79], v[168:171], v[212:215], v[76:79]
	s_barrier
	s_setprio 0
	s_mov_b32 m0, s99
	s_add_u32 s16, s44, 0x40000
	ds_read_b128 v[184:187], v151 offset:16384
	ds_read_b128 v[188:191], v151 offset:17408
	ds_read_b128 v[192:195], v151 offset:18432
	ds_read_b128 v[196:199], v151 offset:19456
	ds_read_b128 v[200:203], v151 offset:20480
	ds_read_b128 v[204:207], v151 offset:21504
	ds_read_b128 v[208:211], v151 offset:22528
	ds_read_b128 v[212:215], v151 offset:23552
	global_load_lds_dwordx4 v136, s[44:45]
	s_mov_b32 m0, vcc_lo
	s_addc_u32 s17, s45, 0
	global_load_lds_dwordx4 v140, s[44:45]
	s_mov_b32 m0, vcc_hi
	s_nop 0
	global_load_lds_dwordx4 v136, s[16:17]
	s_mov_b32 m0, s30
	s_nop 0
	global_load_lds_dwordx4 v140, s[16:17]
	s_mov_b32 m0, s22
	s_nop 0
	global_load_lds_dwordx4 v134, s[28:29]
	s_mov_b32 m0, s23
	s_nop 0
	global_load_lds_dwordx4 v138, s[28:29]
	s_setprio 1
	s_waitcnt vmcnt(8)
	s_waitcnt lgkmcnt(0)
	s_barrier
	s_waitcnt lgkmcnt(0)
	v_mfma_f32_16x16x32_bf16 v[52:55], v[146:149], v[184:187], v[52:55]
	v_mfma_f32_16x16x32_bf16 v[48:51], v[156:159], v[184:187], v[48:51]
	v_mfma_f32_16x16x32_bf16 v[32:35], v[156:159], v[192:195], v[32:35]
	v_mfma_f32_16x16x32_bf16 v[36:39], v[146:149], v[192:195], v[36:39]
	v_mfma_f32_16x16x32_bf16 v[20:23], v[146:149], v[200:203], v[20:23]
	v_mfma_f32_16x16x32_bf16 v[16:19], v[156:159], v[200:203], v[16:19]
	v_mfma_f32_16x16x32_bf16 v[0:3], v[156:159], v[208:211], v[0:3]
	v_mfma_f32_16x16x32_bf16 v[4:7], v[146:149], v[208:211], v[4:7]
	v_mfma_f32_16x16x32_bf16 v[52:55], v[152:155], v[188:191], v[52:55]
	v_mfma_f32_16x16x32_bf16 v[48:51], v[160:163], v[188:191], v[48:51]
	v_mfma_f32_16x16x32_bf16 v[32:35], v[160:163], v[196:199], v[32:35]
	v_mfma_f32_16x16x32_bf16 v[36:39], v[152:155], v[196:199], v[36:39]
	v_mfma_f32_16x16x32_bf16 v[20:23], v[152:155], v[204:207], v[20:23]
	v_mfma_f32_16x16x32_bf16 v[16:19], v[160:163], v[204:207], v[16:19]
	v_mfma_f32_16x16x32_bf16 v[0:3], v[160:163], v[212:215], v[0:3]
	v_mfma_f32_16x16x32_bf16 v[4:7], v[152:155], v[212:215], v[4:7]
	v_mfma_f32_16x16x32_bf16 v[60:63], v[164:167], v[184:187], v[60:63]
	v_mfma_f32_16x16x32_bf16 v[56:59], v[172:175], v[184:187], v[56:59]
	v_mfma_f32_16x16x32_bf16 v[40:43], v[172:175], v[192:195], v[40:43]
	v_mfma_f32_16x16x32_bf16 v[44:47], v[164:167], v[192:195], v[44:47]
	v_mfma_f32_16x16x32_bf16 v[28:31], v[164:167], v[200:203], v[28:31]
	v_mfma_f32_16x16x32_bf16 v[24:27], v[172:175], v[200:203], v[24:27]
	v_mfma_f32_16x16x32_bf16 v[8:11], v[172:175], v[208:211], v[8:11]
	v_mfma_f32_16x16x32_bf16 v[12:15], v[164:167], v[208:211], v[12:15]
	v_mfma_f32_16x16x32_bf16 v[60:63], v[168:171], v[188:191], v[60:63]
	v_mfma_f32_16x16x32_bf16 v[56:59], v[180:183], v[188:191], v[56:59]
	v_mfma_f32_16x16x32_bf16 v[40:43], v[180:183], v[196:199], v[40:43]
	v_mfma_f32_16x16x32_bf16 v[44:47], v[168:171], v[196:199], v[44:47]
	v_mfma_f32_16x16x32_bf16 v[28:31], v[168:171], v[204:207], v[28:31]
	v_mfma_f32_16x16x32_bf16 v[24:27], v[180:183], v[204:207], v[24:27]
	v_mfma_f32_16x16x32_bf16 v[8:11], v[180:183], v[212:215], v[8:11]
	v_mfma_f32_16x16x32_bf16 v[12:15], v[168:171], v[212:215], v[12:15]
	s_barrier
; #define PG8_BAR __builtin_amdgcn_s_barrier()
; template <class Epi, class Sched, bool ALIGN_EPI = false, bool SP2 = false>
; __device__ __forceinline__ void gemm_phase(PG8_LAS unsigned char* lds, const Gemm g, const Sched& S, const Epi& E) {
;     ...
;         for (int t = (Epi::PEEL ? 2 : 0); t < nt; t += 2) {
;             const bool last = (t == nt - 2);
;             const char* a1 = cA + (size_t)(t + 1) * kstepA;
;             const char* a2 = last ? nA : cA + (size_t)(t + 2) * kstepA; const char* b2 = last ? nB : cB + (size_t)(t + 2) * kstepB;
;             const char* a3 = a2 + kstepA; const char* b3 = b2 + kstepB;
;             PG8_ITER(8);
;         }
;     ...
;         if constexpr (ALIGN_EPI) { if (wr == 0) PG8_BAR; }
	s_setprio 0
	ds_read_b128 v[146:149], v132
	ds_read_b128 v[152:155], v132 offset:1024
	ds_read_b128 v[156:159], v132 offset:2048
	ds_read_b128 v[160:163], v132 offset:3072
	ds_read_b128 v[164:167], v133
	ds_read_b128 v[168:171], v133 offset:1024
	ds_read_b128 v[172:175], v133 offset:2048
	ds_read_b128 v[180:183], v133 offset:3072
	s_add_u32 s16, s28, 0x4000
	s_addc_u32 s17, s29, 0
	s_mov_b32 m0, s39
	ds_read_b128 v[184:187], v151 offset:32768
	ds_read_b128 v[188:191], v151 offset:33792
	ds_read_b128 v[192:195], v151 offset:34816
	ds_read_b128 v[196:199], v151 offset:35840
	ds_read_b128 v[200:203], v151 offset:36864
	ds_read_b128 v[204:207], v151 offset:37888
	ds_read_b128 v[208:211], v151 offset:38912
	ds_read_b128 v[212:215], v151 offset:39936
	global_load_lds_dwordx4 v134, s[16:17]
	s_mov_b32 m0, s56
	s_nop 0
	global_load_lds_dwordx4 v138, s[16:17]
	s_setprio 1
	s_waitcnt vmcnt(8)
	s_waitcnt lgkmcnt(0)
	s_barrier
	s_waitcnt lgkmcnt(0)
	v_mfma_f32_16x16x32_bf16 v[118:121], v[146:149], v[184:187], v[118:121]
	v_mfma_f32_16x16x32_bf16 v[114:117], v[156:159], v[184:187], v[114:117]
	v_mfma_f32_16x16x32_bf16 v[98:101], v[156:159], v[192:195], v[98:101]
	v_mfma_f32_16x16x32_bf16 v[102:105], v[146:149], v[192:195], v[102:105]
	v_mfma_f32_16x16x32_bf16 v[84:87], v[146:149], v[200:203], v[84:87]
	v_mfma_f32_16x16x32_bf16 v[80:83], v[156:159], v[200:203], v[80:83]
	v_mfma_f32_16x16x32_bf16 v[64:67], v[156:159], v[208:211], v[64:67]
	v_mfma_f32_16x16x32_bf16 v[68:71], v[146:149], v[208:211], v[68:71]
	v_mfma_f32_16x16x32_bf16 v[118:121], v[152:155], v[188:191], v[118:121]
	v_mfma_f32_16x16x32_bf16 v[114:117], v[160:163], v[188:191], v[114:117]
	v_mfma_f32_16x16x32_bf16 v[98:101], v[160:163], v[196:199], v[98:101]
	v_mfma_f32_16x16x32_bf16 v[102:105], v[152:155], v[196:199], v[102:105]
	v_mfma_f32_16x16x32_bf16 v[84:87], v[152:155], v[204:207], v[84:87]
	v_mfma_f32_16x16x32_bf16 v[80:83], v[160:163], v[204:207], v[80:83]
	v_mfma_f32_16x16x32_bf16 v[64:67], v[160:163], v[212:215], v[64:67]
	v_mfma_f32_16x16x32_bf16 v[68:71], v[152:155], v[212:215], v[68:71]
	v_mfma_f32_16x16x32_bf16 v[126:129], v[164:167], v[184:187], v[126:129]
	v_mfma_f32_16x16x32_bf16 v[122:125], v[172:175], v[184:187], v[122:125]
	v_mfma_f32_16x16x32_bf16 v[106:109], v[172:175], v[192:195], v[106:109]
	v_mfma_f32_16x16x32_bf16 v[110:113], v[164:167], v[192:195], v[110:113]
	v_mfma_f32_16x16x32_bf16 v[92:95], v[164:167], v[200:203], v[92:95]
	v_mfma_f32_16x16x32_bf16 v[88:91], v[172:175], v[200:203], v[88:91]
	v_mfma_f32_16x16x32_bf16 v[72:75], v[172:175], v[208:211], v[72:75]
	v_mfma_f32_16x16x32_bf16 v[76:79], v[164:167], v[208:211], v[76:79]
	v_mfma_f32_16x16x32_bf16 v[126:129], v[168:171], v[188:191], v[126:129]
	v_mfma_f32_16x16x32_bf16 v[122:125], v[180:183], v[188:191], v[122:125]
	v_mfma_f32_16x16x32_bf16 v[106:109], v[180:183], v[196:199], v[106:109]
	v_mfma_f32_16x16x32_bf16 v[110:113], v[168:171], v[196:199], v[110:113]
	v_mfma_f32_16x16x32_bf16 v[92:95], v[168:171], v[204:207], v[92:95]
	v_mfma_f32_16x16x32_bf16 v[88:91], v[180:183], v[204:207], v[88:91]
	v_mfma_f32_16x16x32_bf16 v[72:75], v[180:183], v[212:215], v[72:75]
	v_mfma_f32_16x16x32_bf16 v[76:79], v[168:171], v[212:215], v[76:79]
	s_barrier
	s_setprio 0
	s_mov_b32 m0, s31
	s_add_u32 s100, s44, 0x80
	s_addc_u32 s101, s45, 0
	s_add_u32 s16, s44, 0x40080
	ds_read_b128 v[184:187], v151 offset:49152
	ds_read_b128 v[188:191], v151 offset:50176
	ds_read_b128 v[192:195], v151 offset:51200
	ds_read_b128 v[196:199], v151 offset:52224
	ds_read_b128 v[200:203], v151 offset:53248
	ds_read_b128 v[204:207], v151 offset:54272
	ds_read_b128 v[208:211], v151 offset:55296
	ds_read_b128 v[212:215], v151 offset:56320
	global_load_lds_dwordx4 v136, s[100:101]
	s_mov_b32 m0, s12
	s_addc_u32 s17, s45, 0
	global_load_lds_dwordx4 v140, s[100:101]
	s_mov_b32 m0, s13
	s_nop 0
	global_load_lds_dwordx4 v136, s[16:17]
	s_mov_b32 m0, s11
	s_nop 0
	global_load_lds_dwordx4 v140, s[16:17]
	s_mov_b32 m0, s59
	s_nop 0
	global_load_lds_dwordx4 v134, s[42:43]
	s_mov_b32 m0, s96
	s_nop 0
	global_load_lds_dwordx4 v138, s[42:43]
	s_setprio 1
	s_waitcnt vmcnt(8)
	s_waitcnt lgkmcnt(0)
	s_barrier
	s_waitcnt lgkmcnt(0)
	v_mfma_f32_16x16x32_bf16 v[52:55], v[146:149], v[184:187], v[52:55]
	v_mfma_f32_16x16x32_bf16 v[48:51], v[156:159], v[184:187], v[48:51]
	v_mfma_f32_16x16x32_bf16 v[32:35], v[156:159], v[192:195], v[32:35]
	v_mfma_f32_16x16x32_bf16 v[36:39], v[146:149], v[192:195], v[36:39]
	v_mfma_f32_16x16x32_bf16 v[20:23], v[146:149], v[200:203], v[20:23]
	v_mfma_f32_16x16x32_bf16 v[16:19], v[156:159], v[200:203], v[16:19]
	v_mfma_f32_16x16x32_bf16 v[0:3], v[156:159], v[208:211], v[0:3]
	v_mfma_f32_16x16x32_bf16 v[4:7], v[146:149], v[208:211], v[4:7]
	v_mfma_f32_16x16x32_bf16 v[52:55], v[152:155], v[188:191], v[52:55]
	v_mfma_f32_16x16x32_bf16 v[48:51], v[160:163], v[188:191], v[48:51]
	v_mfma_f32_16x16x32_bf16 v[32:35], v[160:163], v[196:199], v[32:35]
	v_mfma_f32_16x16x32_bf16 v[36:39], v[152:155], v[196:199], v[36:39]
	v_mfma_f32_16x16x32_bf16 v[20:23], v[152:155], v[204:207], v[20:23]
	v_mfma_f32_16x16x32_bf16 v[16:19], v[160:163], v[204:207], v[16:19]
	v_mfma_f32_16x16x32_bf16 v[0:3], v[160:163], v[212:215], v[0:3]
	v_mfma_f32_16x16x32_bf16 v[4:7], v[152:155], v[212:215], v[4:7]
	v_mfma_f32_16x16x32_bf16 v[60:63], v[164:167], v[184:187], v[60:63]
	v_mfma_f32_16x16x32_bf16 v[56:59], v[172:175], v[184:187], v[56:59]
	v_mfma_f32_16x16x32_bf16 v[40:43], v[172:175], v[192:195], v[40:43]
	v_mfma_f32_16x16x32_bf16 v[44:47], v[164:167], v[192:195], v[44:47]
	v_mfma_f32_16x16x32_bf16 v[28:31], v[164:167], v[200:203], v[28:31]
	v_mfma_f32_16x16x32_bf16 v[24:27], v[172:175], v[200:203], v[24:27]
	v_mfma_f32_16x16x32_bf16 v[8:11], v[172:175], v[208:211], v[8:11]
	v_mfma_f32_16x16x32_bf16 v[12:15], v[164:167], v[208:211], v[12:15]
	v_mfma_f32_16x16x32_bf16 v[60:63], v[168:171], v[188:191], v[60:63]
	v_mfma_f32_16x16x32_bf16 v[56:59], v[180:183], v[188:191], v[56:59]
	v_mfma_f32_16x16x32_bf16 v[40:43], v[180:183], v[196:199], v[40:43]
	v_mfma_f32_16x16x32_bf16 v[44:47], v[168:171], v[196:199], v[44:47]
	v_mfma_f32_16x16x32_bf16 v[28:31], v[168:171], v[204:207], v[28:31]
	v_mfma_f32_16x16x32_bf16 v[24:27], v[180:183], v[204:207], v[24:27]
	v_mfma_f32_16x16x32_bf16 v[8:11], v[180:183], v[212:215], v[8:11]
	v_mfma_f32_16x16x32_bf16 v[12:15], v[168:171], v[212:215], v[12:15]
	s_barrier
	s_setprio 0
	s_add_i32 s18, s18, 2
	s_add_u32 s3, s3, 0x100
	s_addc_u32 s2, s2, 0
	s_add_u32 s24, s24, 0x800000
	s_addc_u32 s25, s25, 0
	s_cmp_gt_u32 s18, 13
	s_cbranch_scc0 .LBB0_250
	v_readlane_b32 s2, v255, 33
	v_readlane_b32 s3, v255, 34
	v_readlane_b32 s12, v255, 31
	s_and_b64 vcc, exec, s[2:3]
	v_readlane_b32 s13, v255, 32
	s_cbranch_vccz .LBB0_253
	s_barrier

; template <class Epi, class Sched, bool ALIGN_EPI = false, bool SP2 = false>
; __device__ __forceinline__ void gemm_phase(PG8_LAS unsigned char* lds, const Gemm g, const Sched& S, const Epi& E) {
;     ...
;         for (int t = (Epi::PEEL ? 2 : 0); t < nt; t += 2) {
;             const bool last = (t == nt - 2);
;             const char* a1 = cA + (size_t)(t + 1) * kstepA;
;             const char* a2 = last ? nA : cA + (size_t)(t + 2) * kstepA; const char* b2 = last ? nB : cB + (size_t)(t + 2) * kstepB;
;             const char* a3 = a2 + kstepA; const char* b3 = b2 + kstepB;
;             PG8_ITER(8);
.LBB0_345:
	s_add_i32 s10, s10, 2
	s_add_u32 s44, s42, s34
	s_addc_u32 s45, s43, s35
	s_add_i32 s18, 0, 0x10000
	s_and_b64 s[2:3], exec, s[46:47]
	s_cselect_b32 s3, s13, s59
	s_cselect_b32 s2, s12, s58
	s_add_i32 s38, 0, 0x14000
	v_add_u32_e32 v142, s18, v97
	v_add_u32_e32 v170, s38, v97
	ds_read_b128 v[122:125], v142
	ds_read_b128 v[126:129], v142 offset:1024
	ds_read_b128 v[138:141], v142 offset:2048
	ds_read_b128 v[142:145], v142 offset:3072
	ds_read_b128 v[146:149], v170
	ds_read_b128 v[150:153], v170 offset:1024
	ds_read_b128 v[154:157], v170 offset:2048
	ds_read_b128 v[170:173], v170 offset:3072
	s_add_i32 m0, s97, 0xc000
	ds_read_b128 v[174:177], v188
	ds_read_b128 v[180:183], v188 offset:1024
	ds_read_b128 v[184:187], v188 offset:2048
	ds_read_b128 v[190:193], v188 offset:3072
	ds_read_b128 v[194:197], v188 offset:4096
	ds_read_b128 v[198:201], v188 offset:5120
	ds_read_b128 v[202:205], v188 offset:6144
	ds_read_b128 v[206:209], v188 offset:7168
	global_load_lds_dwordx4 v168, s[24:25]
	s_add_i32 m0, s97, 0xe000
	s_nop 0
	global_load_lds_dwordx4 v166, s[24:25]
	s_setprio 1
	s_waitcnt vmcnt(8)
	s_waitcnt lgkmcnt(0)
	s_barrier
	s_waitcnt lgkmcnt(0)
	v_mfma_f32_16x16x32_bf16 v[134:137], v[122:125], v[174:177], v[134:137]
	v_mfma_f32_16x16x32_bf16 v[130:133], v[138:141], v[174:177], v[130:133]
	v_mfma_f32_16x16x32_bf16 v[106:109], v[138:141], v[184:187], v[106:109]
	v_mfma_f32_16x16x32_bf16 v[110:113], v[122:125], v[184:187], v[110:113]
	v_mfma_f32_16x16x32_bf16 v[92:95], v[122:125], v[194:197], v[92:95]
	v_mfma_f32_16x16x32_bf16 v[88:91], v[138:141], v[194:197], v[88:91]
	v_mfma_f32_16x16x32_bf16 v[72:75], v[138:141], v[202:205], v[72:75]
	v_mfma_f32_16x16x32_bf16 v[76:79], v[122:125], v[202:205], v[76:79]
	v_mfma_f32_16x16x32_bf16 v[134:137], v[126:129], v[180:183], v[134:137]
	v_mfma_f32_16x16x32_bf16 v[130:133], v[142:145], v[180:183], v[130:133]
	v_mfma_f32_16x16x32_bf16 v[106:109], v[142:145], v[190:193], v[106:109]
	v_mfma_f32_16x16x32_bf16 v[110:113], v[126:129], v[190:193], v[110:113]
	v_mfma_f32_16x16x32_bf16 v[92:95], v[126:129], v[198:201], v[92:95]
	v_mfma_f32_16x16x32_bf16 v[88:91], v[142:145], v[198:201], v[88:91]
	v_mfma_f32_16x16x32_bf16 v[72:75], v[142:145], v[206:209], v[72:75]
	v_mfma_f32_16x16x32_bf16 v[76:79], v[126:129], v[206:209], v[76:79]
	v_mfma_f32_16x16x32_bf16 v[118:121], v[146:149], v[174:177], v[118:121]
	v_mfma_f32_16x16x32_bf16 v[114:117], v[154:157], v[174:177], v[114:117]
	v_mfma_f32_16x16x32_bf16 v[98:101], v[154:157], v[184:187], v[98:101]
	v_mfma_f32_16x16x32_bf16 v[102:105], v[146:149], v[184:187], v[102:105]
	v_mfma_f32_16x16x32_bf16 v[84:87], v[146:149], v[194:197], v[84:87]
	v_mfma_f32_16x16x32_bf16 v[80:83], v[154:157], v[194:197], v[80:83]
	v_mfma_f32_16x16x32_bf16 v[64:67], v[154:157], v[202:205], v[64:67]
	v_mfma_f32_16x16x32_bf16 v[68:71], v[146:149], v[202:205], v[68:71]
	v_mfma_f32_16x16x32_bf16 v[118:121], v[150:153], v[180:183], v[118:121]
	v_mfma_f32_16x16x32_bf16 v[114:117], v[170:173], v[180:183], v[114:117]
	v_mfma_f32_16x16x32_bf16 v[98:101], v[170:173], v[190:193], v[98:101]
	v_mfma_f32_16x16x32_bf16 v[102:105], v[150:153], v[190:193], v[102:105]
	v_mfma_f32_16x16x32_bf16 v[84:87], v[150:153], v[198:201], v[84:87]
	v_mfma_f32_16x16x32_bf16 v[80:83], v[170:173], v[198:201], v[80:83]
	v_mfma_f32_16x16x32_bf16 v[64:67], v[170:173], v[206:209], v[64:67]
	v_mfma_f32_16x16x32_bf16 v[68:71], v[150:153], v[206:209], v[68:71]
	s_barrier
	s_setprio 0
	s_add_i32 s18, s18, s96
	v_lshl_add_u64 v[178:179], s[2:3], 0, v[162:163]
	s_mov_b32 m0, s18
	ds_read_b128 v[174:177], v188 offset:16384
	ds_read_b128 v[180:183], v188 offset:17408
	ds_read_b128 v[184:187], v188 offset:18432
	ds_read_b128 v[190:193], v188 offset:19456
	ds_read_b128 v[194:197], v188 offset:20480
	ds_read_b128 v[198:201], v188 offset:21504
	ds_read_b128 v[202:205], v188 offset:22528
	ds_read_b128 v[206:209], v188 offset:23552
	global_load_lds_dwordx4 v162, s[2:3]
	s_add_i32 m0, s18, 0x2000
	v_lshl_add_u64 v[210:211], s[2:3], 0, v[158:159]
	s_add_u32 s2, s2, s48
	s_addc_u32 s3, s3, 0
	s_add_i32 s18, s38, s96
	global_load_lds_dwordx4 v[210:211], off
	v_lshl_add_u64 v[212:213], s[2:3], 0, v[162:163]
	s_mov_b32 m0, s18
	v_lshl_add_u64 v[214:215], s[2:3], 0, v[158:159]
	global_load_lds_dwordx4 v162, s[2:3]
	s_add_i32 m0, s18, 0x2000
	s_nop 0
	global_load_lds_dwordx4 v158, s[2:3]
	s_mov_b32 m0, s97
	s_nop 0
	global_load_lds_dwordx4 v164, s[42:43]
	s_mov_b32 m0, s22
	s_nop 0
	global_load_lds_dwordx4 v160, s[42:43]
	s_setprio 1
	s_waitcnt vmcnt(8)
	s_waitcnt lgkmcnt(0)
	s_barrier
	s_waitcnt lgkmcnt(0)
	v_mfma_f32_16x16x32_bf16 v[60:63], v[122:125], v[174:177], v[60:63]
	v_mfma_f32_16x16x32_bf16 v[56:59], v[138:141], v[174:177], v[56:59]
	v_mfma_f32_16x16x32_bf16 v[40:43], v[138:141], v[184:187], v[40:43]
	v_mfma_f32_16x16x32_bf16 v[44:47], v[122:125], v[184:187], v[44:47]
	v_mfma_f32_16x16x32_bf16 v[28:31], v[122:125], v[194:197], v[28:31]
	v_mfma_f32_16x16x32_bf16 v[24:27], v[138:141], v[194:197], v[24:27]
	v_mfma_f32_16x16x32_bf16 v[8:11], v[138:141], v[202:205], v[8:11]
	v_mfma_f32_16x16x32_bf16 v[12:15], v[122:125], v[202:205], v[12:15]
	v_mfma_f32_16x16x32_bf16 v[60:63], v[126:129], v[180:183], v[60:63]
	v_mfma_f32_16x16x32_bf16 v[56:59], v[142:145], v[180:183], v[56:59]
	v_mfma_f32_16x16x32_bf16 v[40:43], v[142:145], v[190:193], v[40:43]
	v_mfma_f32_16x16x32_bf16 v[44:47], v[126:129], v[190:193], v[44:47]
	v_mfma_f32_16x16x32_bf16 v[28:31], v[126:129], v[198:201], v[28:31]
	v_mfma_f32_16x16x32_bf16 v[24:27], v[142:145], v[198:201], v[24:27]
	v_mfma_f32_16x16x32_bf16 v[8:11], v[142:145], v[206:209], v[8:11]
	v_mfma_f32_16x16x32_bf16 v[12:15], v[126:129], v[206:209], v[12:15]
	v_mfma_f32_16x16x32_bf16 v[52:55], v[146:149], v[174:177], v[52:55]
	v_mfma_f32_16x16x32_bf16 v[48:51], v[154:157], v[174:177], v[48:51]
	v_mfma_f32_16x16x32_bf16 v[32:35], v[154:157], v[184:187], v[32:35]
	v_mfma_f32_16x16x32_bf16 v[36:39], v[146:149], v[184:187], v[36:39]
	v_mfma_f32_16x16x32_bf16 v[20:23], v[146:149], v[194:197], v[20:23]
	v_mfma_f32_16x16x32_bf16 v[16:19], v[154:157], v[194:197], v[16:19]
	v_mfma_f32_16x16x32_bf16 v[0:3], v[154:157], v[202:205], v[0:3]
	v_mfma_f32_16x16x32_bf16 v[4:7], v[146:149], v[202:205], v[4:7]
	v_mfma_f32_16x16x32_bf16 v[52:55], v[150:153], v[180:183], v[52:55]
	v_mfma_f32_16x16x32_bf16 v[48:51], v[170:173], v[180:183], v[48:51]
	v_mfma_f32_16x16x32_bf16 v[32:35], v[170:173], v[190:193], v[32:35]
	v_mfma_f32_16x16x32_bf16 v[36:39], v[150:153], v[190:193], v[36:39]
	v_mfma_f32_16x16x32_bf16 v[20:23], v[150:153], v[198:201], v[20:23]
	v_mfma_f32_16x16x32_bf16 v[16:19], v[170:173], v[198:201], v[16:19]
	v_mfma_f32_16x16x32_bf16 v[0:3], v[170:173], v[206:209], v[0:3]
	v_mfma_f32_16x16x32_bf16 v[4:7], v[150:153], v[206:209], v[4:7]
	s_barrier
	s_setprio 0
	s_add_i32 s18, 0, 0x18000
	s_add_i32 s38, 0, 0x1c000
	v_add_u32_e32 v142, s18, v97
	v_add_u32_e32 v170, s38, v97
	ds_read_b128 v[122:125], v142
	ds_read_b128 v[126:129], v142 offset:1024
	ds_read_b128 v[138:141], v142 offset:2048
	ds_read_b128 v[142:145], v142 offset:3072
	ds_read_b128 v[146:149], v170
	ds_read_b128 v[150:153], v170 offset:1024
	ds_read_b128 v[154:157], v170 offset:2048
	ds_read_b128 v[170:173], v170 offset:3072
	s_add_u32 s2, s42, s98
	s_addc_u32 s3, s43, 0
	s_mov_b32 m0, s23
	ds_read_b128 v[174:177], v188 offset:32768
	ds_read_b128 v[180:183], v188 offset:33792
	ds_read_b128 v[184:187], v188 offset:34816
	ds_read_b128 v[190:193], v188 offset:35840
	ds_read_b128 v[194:197], v188 offset:36864
	ds_read_b128 v[198:201], v188 offset:37888
	ds_read_b128 v[202:205], v188 offset:38912
	ds_read_b128 v[206:209], v188 offset:39936
	global_load_lds_dwordx4 v164, s[2:3]
	s_mov_b32 m0, s19
	s_nop 0
	global_load_lds_dwordx4 v160, s[2:3]
	s_setprio 1
	s_waitcnt vmcnt(8)
	s_waitcnt lgkmcnt(0)
	s_barrier
	s_waitcnt lgkmcnt(0)
	v_mfma_f32_16x16x32_bf16 v[134:137], v[122:125], v[174:177], v[134:137]
	v_mfma_f32_16x16x32_bf16 v[130:133], v[138:141], v[174:177], v[130:133]
	v_mfma_f32_16x16x32_bf16 v[106:109], v[138:141], v[184:187], v[106:109]
	v_mfma_f32_16x16x32_bf16 v[110:113], v[122:125], v[184:187], v[110:113]
	v_mfma_f32_16x16x32_bf16 v[92:95], v[122:125], v[194:197], v[92:95]
	v_mfma_f32_16x16x32_bf16 v[88:91], v[138:141], v[194:197], v[88:91]
	v_mfma_f32_16x16x32_bf16 v[72:75], v[138:141], v[202:205], v[72:75]
	v_mfma_f32_16x16x32_bf16 v[76:79], v[122:125], v[202:205], v[76:79]
	v_mfma_f32_16x16x32_bf16 v[134:137], v[126:129], v[180:183], v[134:137]
	v_mfma_f32_16x16x32_bf16 v[130:133], v[142:145], v[180:183], v[130:133]
	v_mfma_f32_16x16x32_bf16 v[106:109], v[142:145], v[190:193], v[106:109]
	v_mfma_f32_16x16x32_bf16 v[110:113], v[126:129], v[190:193], v[110:113]
	v_mfma_f32_16x16x32_bf16 v[92:95], v[126:129], v[198:201], v[92:95]
	v_mfma_f32_16x16x32_bf16 v[88:91], v[142:145], v[198:201], v[88:91]
	v_mfma_f32_16x16x32_bf16 v[72:75], v[142:145], v[206:209], v[72:75]
	v_mfma_f32_16x16x32_bf16 v[76:79], v[126:129], v[206:209], v[76:79]
	v_mfma_f32_16x16x32_bf16 v[118:121], v[146:149], v[174:177], v[118:121]
	v_mfma_f32_16x16x32_bf16 v[114:117], v[154:157], v[174:177], v[114:117]
	v_mfma_f32_16x16x32_bf16 v[98:101], v[154:157], v[184:187], v[98:101]
	v_mfma_f32_16x16x32_bf16 v[102:105], v[146:149], v[184:187], v[102:105]
	v_mfma_f32_16x16x32_bf16 v[84:87], v[146:149], v[194:197], v[84:87]
	v_mfma_f32_16x16x32_bf16 v[80:83], v[154:157], v[194:197], v[80:83]
	v_mfma_f32_16x16x32_bf16 v[64:67], v[154:157], v[202:205], v[64:67]
	v_mfma_f32_16x16x32_bf16 v[68:71], v[146:149], v[202:205], v[68:71]
	v_mfma_f32_16x16x32_bf16 v[118:121], v[150:153], v[180:183], v[118:121]
	v_mfma_f32_16x16x32_bf16 v[114:117], v[170:173], v[180:183], v[114:117]
	v_mfma_f32_16x16x32_bf16 v[98:101], v[170:173], v[190:193], v[98:101]
	v_mfma_f32_16x16x32_bf16 v[102:105], v[150:153], v[190:193], v[102:105]
	v_mfma_f32_16x16x32_bf16 v[84:87], v[150:153], v[198:201], v[84:87]
	v_mfma_f32_16x16x32_bf16 v[80:83], v[170:173], v[198:201], v[80:83]
	v_mfma_f32_16x16x32_bf16 v[64:67], v[170:173], v[206:209], v[64:67]
	v_mfma_f32_16x16x32_bf16 v[68:71], v[150:153], v[206:209], v[68:71]
	s_barrier
; template <class Epi, class Sched, bool ALIGN_EPI = false, bool SP2 = false>
; __device__ __forceinline__ void gemm_phase(PG8_LAS unsigned char* lds, const Gemm g, const Sched& S, const Epi& E) {
;     ...
;         for (int t = (Epi::PEEL ? 2 : 0); t < nt; t += 2) {
;             const bool last = (t == nt - 2);
;             const char* a1 = cA + (size_t)(t + 1) * kstepA;
;             const char* a2 = last ? nA : cA + (size_t)(t + 2) * kstepA; const char* b2 = last ? nB : cB + (size_t)(t + 2) * kstepB;
;             const char* a3 = a2 + kstepA; const char* b3 = b2 + kstepB;
;             PG8_ITER(8);
;         }
	s_setprio 0
	s_add_i32 s2, s18, s96
	v_lshl_add_u64 v[178:179], v[178:179], 0, s[36:37]
	s_mov_b32 m0, s2
	ds_read_b128 v[174:177], v188 offset:49152
	ds_read_b128 v[180:183], v188 offset:50176
	ds_read_b128 v[184:187], v188 offset:51200
	ds_read_b128 v[190:193], v188 offset:52224
	ds_read_b128 v[194:197], v188 offset:53248
	ds_read_b128 v[198:201], v188 offset:54272
	ds_read_b128 v[202:205], v188 offset:55296
	ds_read_b128 v[206:209], v188 offset:56320
	global_load_lds_dwordx4 v[178:179], off
	v_lshl_add_u64 v[178:179], v[210:211], 0, s[36:37]
	s_add_i32 m0, s2, 0x2000
	s_add_i32 s2, s38, s96
	global_load_lds_dwordx4 v[178:179], off
	v_lshl_add_u64 v[178:179], v[212:213], 0, s[36:37]
	s_mov_b32 m0, s2
	s_nop 0
	global_load_lds_dwordx4 v[178:179], off
	v_lshl_add_u64 v[178:179], v[214:215], 0, s[36:37]
	s_add_i32 m0, s2, 0x2000
	s_nop 0
	global_load_lds_dwordx4 v[178:179], off
	s_mov_b32 m0, s6
	s_nop 0
	global_load_lds_dwordx4 v164, s[44:45]
	s_mov_b32 m0, s56
	s_nop 0
	global_load_lds_dwordx4 v160, s[44:45]
	s_setprio 1
	s_waitcnt vmcnt(8)
	s_waitcnt lgkmcnt(0)
	s_barrier
	s_waitcnt lgkmcnt(0)
	v_mfma_f32_16x16x32_bf16 v[60:63], v[122:125], v[174:177], v[60:63]
	v_mfma_f32_16x16x32_bf16 v[56:59], v[138:141], v[174:177], v[56:59]
	v_mfma_f32_16x16x32_bf16 v[40:43], v[138:141], v[184:187], v[40:43]
	v_mfma_f32_16x16x32_bf16 v[44:47], v[122:125], v[184:187], v[44:47]
	v_mfma_f32_16x16x32_bf16 v[28:31], v[122:125], v[194:197], v[28:31]
	v_mfma_f32_16x16x32_bf16 v[24:27], v[138:141], v[194:197], v[24:27]
	v_mfma_f32_16x16x32_bf16 v[8:11], v[138:141], v[202:205], v[8:11]
	v_mfma_f32_16x16x32_bf16 v[12:15], v[122:125], v[202:205], v[12:15]
	v_mfma_f32_16x16x32_bf16 v[60:63], v[126:129], v[180:183], v[60:63]
	v_mfma_f32_16x16x32_bf16 v[56:59], v[142:145], v[180:183], v[56:59]
	v_mfma_f32_16x16x32_bf16 v[40:43], v[142:145], v[190:193], v[40:43]
	v_mfma_f32_16x16x32_bf16 v[44:47], v[126:129], v[190:193], v[44:47]
	v_mfma_f32_16x16x32_bf16 v[28:31], v[126:129], v[198:201], v[28:31]
	v_mfma_f32_16x16x32_bf16 v[24:27], v[142:145], v[198:201], v[24:27]
	v_mfma_f32_16x16x32_bf16 v[8:11], v[142:145], v[206:209], v[8:11]
	v_mfma_f32_16x16x32_bf16 v[12:15], v[126:129], v[206:209], v[12:15]
	v_mfma_f32_16x16x32_bf16 v[52:55], v[146:149], v[174:177], v[52:55]
	v_mfma_f32_16x16x32_bf16 v[48:51], v[154:157], v[174:177], v[48:51]
	v_mfma_f32_16x16x32_bf16 v[32:35], v[154:157], v[184:187], v[32:35]
	v_mfma_f32_16x16x32_bf16 v[36:39], v[146:149], v[184:187], v[36:39]
	v_mfma_f32_16x16x32_bf16 v[20:23], v[146:149], v[194:197], v[20:23]
	v_mfma_f32_16x16x32_bf16 v[16:19], v[154:157], v[194:197], v[16:19]
	v_mfma_f32_16x16x32_bf16 v[0:3], v[154:157], v[202:205], v[0:3]
	v_mfma_f32_16x16x32_bf16 v[4:7], v[146:149], v[202:205], v[4:7]
	v_mfma_f32_16x16x32_bf16 v[52:55], v[150:153], v[180:183], v[52:55]
	v_mfma_f32_16x16x32_bf16 v[48:51], v[170:173], v[180:183], v[48:51]
	v_mfma_f32_16x16x32_bf16 v[32:35], v[170:173], v[190:193], v[32:35]
	v_mfma_f32_16x16x32_bf16 v[36:39], v[150:153], v[190:193], v[36:39]
	v_mfma_f32_16x16x32_bf16 v[20:23], v[150:153], v[198:201], v[20:23]
	v_mfma_f32_16x16x32_bf16 v[16:19], v[170:173], v[198:201], v[16:19]
	v_mfma_f32_16x16x32_bf16 v[0:3], v[170:173], v[206:209], v[0:3]
	v_mfma_f32_16x16x32_bf16 v[4:7], v[150:153], v[206:209], v[4:7]
	s_barrier
	s_setprio 0
	s_add_u32 s58, s58, 0x100
	s_addc_u32 s59, s59, 0
	s_add_u32 s24, s24, s49
	s_addc_u32 s25, s25, 0
	s_cmp_ge_u32 s10, s8
	s_cbranch_scc1 .LBB0_348

; template <class Epi, class Sched, bool ALIGN_EPI = false, bool SP2 = false>
; __device__ __forceinline__ void gemm_phase(PG8_LAS unsigned char* lds, const Gemm g, const Sched& S, const Epi& E) {
;     ...
;         const bool has_next = S.next(ui + 1, nxt);
;         const char* nA = has_next ? (const char*)g.A + (size_t)nxt.pm * tstepA : cA; const char* nB = has_next ? (const char*)g.Bt + (size_t)nxt.pn * tstepB : cB;
;     ...
;         if constexpr (Epi::PEEL) {
;             const char* a1 = cA + kstepA; const char* a2 = cA + 2 * kstepA; const char* b2 = cB + 2 * kstepB; const char* a3 = a2 + kstepA; const char* b3 = b2 + kstepB;
;             PG8_ITER(8);
.LBB0_477:
	s_ashr_i32 s27, s26, 31
	s_lshl_b64 s[2:3], s[26:27], 15
	v_readlane_b32 s10, v255, 15
	s_add_u32 s28, s10, s2
	v_readlane_b32 s2, v255, 16
	s_addc_u32 s29, s2, s3
	s_ashr_i32 s25, s24, 31
	s_lshl_b64 s[2:3], s[24:25], 19
	s_add_u32 s30, s19, s2
	s_addc_u32 s31, s22, s3
	s_add_u32 s44, s34, 0x800000
	s_addc_u32 s45, s35, 0
	s_add_u32 s42, s34, 0xc00000
	s_addc_u32 s43, s35, 0
	s_add_i32 s61, 0, 0x10000
	s_and_b64 s[2:3], s[40:41], exec
	s_cselect_b32 s25, s29, s35
	s_cselect_b32 s27, s28, s34
	s_add_i32 s97, 0, 0x14000
	v_add_u32_e32 v142, s61, v97
	v_add_u32_e32 v143, s97, v97
	ds_read_b128 v[0:3], v142
	ds_read_b128 v[4:7], v142 offset:1024
	ds_read_b128 v[8:11], v142 offset:2048
	ds_read_b128 v[12:15], v142 offset:3072
	ds_read_b128 v[16:19], v143
	s_waitcnt lgkmcnt(0)
	ds_read_b128 v[20:23], v143 offset:1024
	ds_read_b128 v[24:27], v143 offset:2048
	ds_read_b128 v[28:31], v143 offset:3072
	s_and_b64 s[2:3], s[40:41], exec
	s_cselect_b32 s57, s31, s1
	s_cselect_b32 s58, s30, s0
	s_add_u32 s2, s34, 0x404000
	s_addc_u32 s3, s35, 0
	s_add_i32 s59, s23, 0xc000
	s_mov_b32 m0, s59
	s_add_i32 s60, s23, 0xe000
	ds_read_b128 v[32:35], v156
	ds_read_b128 v[36:39], v156 offset:1024
	ds_read_b128 v[40:43], v156 offset:2048
	ds_read_b128 v[44:47], v156 offset:3072
	ds_read_b128 v[48:51], v156 offset:4096
	ds_read_b128 v[52:55], v156 offset:5120
	ds_read_b128 v[56:59], v156 offset:6144
	ds_read_b128 v[60:63], v156 offset:7168
	global_load_lds_dwordx4 v130, s[2:3]
	s_mov_b32 m0, s60
	s_nop 0
	global_load_lds_dwordx4 v134, s[2:3]
	s_setprio 1
	s_waitcnt vmcnt(8)
	s_waitcnt lgkmcnt(0)
	s_barrier
	s_waitcnt lgkmcnt(0)
	v_mfma_f32_16x16x32_bf16 v[88:91], v[0:3], v[56:59], 0
	v_mfma_f32_16x16x32_bf16 v[64:67], v[0:3], v[32:35], 0
	v_mfma_f32_16x16x32_bf16 v[68:71], v[8:11], v[32:35], 0
	v_mfma_f32_16x16x32_bf16 v[72:75], v[0:3], v[40:43], 0
	v_mfma_f32_16x16x32_bf16 v[76:79], v[8:11], v[40:43], 0
	v_mfma_f32_16x16x32_bf16 v[80:83], v[0:3], v[48:51], 0
	v_mfma_f32_16x16x32_bf16 v[84:87], v[8:11], v[48:51], 0
	v_mfma_f32_16x16x32_bf16 v[92:95], v[4:7], v[60:63], v[88:91]
	v_mfma_f32_16x16x32_bf16 v[88:91], v[8:11], v[56:59], 0
	v_mfma_f32_16x16x32_bf16 v[64:67], v[4:7], v[36:39], v[64:67]
	v_mfma_f32_16x16x32_bf16 v[68:71], v[12:15], v[36:39], v[68:71]
	v_mfma_f32_16x16x32_bf16 v[72:75], v[4:7], v[44:47], v[72:75]
	v_mfma_f32_16x16x32_bf16 v[76:79], v[12:15], v[44:47], v[76:79]
	v_mfma_f32_16x16x32_bf16 v[80:83], v[4:7], v[52:55], v[80:83]
	v_mfma_f32_16x16x32_bf16 v[84:87], v[12:15], v[52:55], v[84:87]
	v_mfma_f32_16x16x32_bf16 v[102:105], v[12:15], v[60:63], v[88:91]
	v_mfma_f32_16x16x32_bf16 v[88:91], v[16:19], v[32:35], 0
	v_mfma_f32_16x16x32_bf16 v[32:35], v[24:27], v[32:35], 0
	v_mfma_f32_16x16x32_bf16 v[110:113], v[20:23], v[36:39], v[88:91]
	v_mfma_f32_16x16x32_bf16 v[32:35], v[28:31], v[36:39], v[32:35]
	v_mfma_f32_16x16x32_bf16 v[36:39], v[16:19], v[40:43], 0
	v_mfma_f32_16x16x32_bf16 v[40:43], v[24:27], v[40:43], 0
	v_mfma_f32_16x16x32_bf16 v[36:39], v[20:23], v[44:47], v[36:39]
	v_mfma_f32_16x16x32_bf16 v[40:43], v[28:31], v[44:47], v[40:43]
	v_mfma_f32_16x16x32_bf16 v[44:47], v[16:19], v[48:51], 0
	v_mfma_f32_16x16x32_bf16 v[48:51], v[24:27], v[48:51], 0
	v_mfma_f32_16x16x32_bf16 v[44:47], v[20:23], v[52:55], v[44:47]
	v_mfma_f32_16x16x32_bf16 v[48:51], v[28:31], v[52:55], v[48:51]
	v_mfma_f32_16x16x32_bf16 v[52:55], v[16:19], v[56:59], 0
	v_mfma_f32_16x16x32_bf16 v[56:59], v[24:27], v[56:59], 0
	v_mfma_f32_16x16x32_bf16 v[52:55], v[20:23], v[60:63], v[52:55]
	v_mfma_f32_16x16x32_bf16 v[56:59], v[28:31], v[60:63], v[56:59]
	s_barrier
	s_setprio 0
	v_lshl_add_u64 v[154:155], s[0:1], 0, v[132:133]
	s_mov_b64 s[2:3], 0x100
	s_add_i32 s61, s61, s9
	v_lshl_add_u64 v[144:145], v[154:155], 0, s[2:3]
	s_mov_b32 m0, s61
	v_lshl_add_u64 v[178:179], s[0:1], 0, v[136:137]
	s_add_i32 s96, s61, 0x2000
	ds_read_b128 v[60:63], v156 offset:16384
	ds_read_b128 v[88:91], v156 offset:17408
	ds_read_b128 v[98:101], v156 offset:18432
	ds_read_b128 v[106:109], v156 offset:19456
	ds_read_b128 v[114:117], v156 offset:20480
	ds_read_b128 v[118:121], v156 offset:21504
	ds_read_b128 v[122:125], v156 offset:22528
	ds_read_b128 v[126:129], v156 offset:23552
	global_load_lds_dwordx4 v[144:145], off
	v_lshl_add_u64 v[144:145], v[178:179], 0, s[2:3]
	s_add_u32 s2, s0, 0x40100
	s_mov_b32 m0, s96
	s_addc_u32 s3, s1, 0
	s_add_i32 s97, s97, s9
	global_load_lds_dwordx4 v[144:145], off
	s_mov_b32 m0, s97
	s_add_i32 s98, s97, 0x2000
	global_load_lds_dwordx4 v132, s[2:3]
	s_mov_b32 m0, s98
	s_nop 0
	global_load_lds_dwordx4 v136, s[2:3]
	s_mov_b32 m0, s23
	s_nop 0
	global_load_lds_dwordx4 v130, s[44:45]
	s_mov_b32 m0, s39
	s_nop 0
	global_load_lds_dwordx4 v134, s[44:45]
	s_setprio 1
	s_waitcnt vmcnt(8)
	s_waitcnt lgkmcnt(0)
	s_barrier
	s_waitcnt lgkmcnt(0)
	v_mfma_f32_16x16x32_bf16 v[144:147], v[0:3], v[60:63], 0
	v_mfma_f32_16x16x32_bf16 v[158:161], v[0:3], v[98:101], 0
	v_mfma_f32_16x16x32_bf16 v[166:169], v[0:3], v[114:117], 0
	v_mfma_f32_16x16x32_bf16 v[0:3], v[0:3], v[122:125], 0
	v_mfma_f32_16x16x32_bf16 v[146:149], v[4:7], v[88:91], v[144:147]
	v_mfma_f32_16x16x32_bf16 v[158:161], v[4:7], v[106:109], v[158:161]
	v_mfma_f32_16x16x32_bf16 v[166:169], v[4:7], v[118:121], v[166:169]
	v_mfma_f32_16x16x32_bf16 v[0:3], v[4:7], v[126:129], v[0:3]
	v_mfma_f32_16x16x32_bf16 v[4:7], v[8:11], v[122:125], 0
	v_mfma_f32_16x16x32_bf16 v[150:153], v[8:11], v[60:63], 0
	v_mfma_f32_16x16x32_bf16 v[162:165], v[8:11], v[98:101], 0
	v_mfma_f32_16x16x32_bf16 v[170:173], v[8:11], v[114:117], 0
	v_mfma_f32_16x16x32_bf16 v[4:7], v[12:15], v[126:129], v[4:7]
	v_mfma_f32_16x16x32_bf16 v[150:153], v[12:15], v[88:91], v[150:153]
	v_mfma_f32_16x16x32_bf16 v[162:165], v[12:15], v[106:109], v[162:165]
	v_mfma_f32_16x16x32_bf16 v[170:173], v[12:15], v[118:121], v[170:173]
	v_mfma_f32_16x16x32_bf16 v[8:11], v[16:19], v[60:63], 0
	v_mfma_f32_16x16x32_bf16 v[12:15], v[20:23], v[88:91], v[8:11]
	v_mfma_f32_16x16x32_bf16 v[8:11], v[24:27], v[60:63], 0
	v_mfma_f32_16x16x32_bf16 v[174:177], v[28:31], v[88:91], v[8:11]
	v_mfma_f32_16x16x32_bf16 v[8:11], v[16:19], v[98:101], 0
	v_mfma_f32_16x16x32_bf16 v[188:191], v[20:23], v[106:109], v[8:11]
	v_mfma_f32_16x16x32_bf16 v[8:11], v[24:27], v[98:101], 0
	v_mfma_f32_16x16x32_bf16 v[192:195], v[28:31], v[106:109], v[8:11]
	v_mfma_f32_16x16x32_bf16 v[8:11], v[16:19], v[114:117], 0
	v_mfma_f32_16x16x32_bf16 v[196:199], v[20:23], v[118:121], v[8:11]
	v_mfma_f32_16x16x32_bf16 v[8:11], v[24:27], v[114:117], 0
	v_mfma_f32_16x16x32_bf16 v[200:203], v[28:31], v[118:121], v[8:11]
	v_mfma_f32_16x16x32_bf16 v[8:11], v[16:19], v[122:125], 0
	v_mfma_f32_16x16x32_bf16 v[204:207], v[20:23], v[126:129], v[8:11]
	v_mfma_f32_16x16x32_bf16 v[8:11], v[24:27], v[122:125], 0
	v_mfma_f32_16x16x32_bf16 v[208:211], v[28:31], v[126:129], v[8:11]
	s_barrier
	s_setprio 0
	s_add_i32 s99, 0, 0x18000
	s_add_i32 vcc_hi, 0, 0x1c000
	v_add_u32_e32 v144, s99, v97
	v_add_u32_e32 v145, vcc_hi, v97
	s_nop 0
	ds_read_b128 v[8:11], v144
	ds_read_b128 v[20:23], v144 offset:1024
	ds_read_b128 v[28:31], v144 offset:2048
	ds_read_b128 v[212:215], v144 offset:3072
	ds_read_b128 v[216:219], v145
	ds_read_b128 v[220:223], v145 offset:1024
	ds_read_b128 v[234:237], v145 offset:2048
	ds_read_b128 v[238:241], v145 offset:3072
	s_add_u32 s2, s34, 0x804000
	s_addc_u32 s3, s35, 0
	s_mov_b32 m0, s46
	ds_read_b128 v[16:19], v156 offset:32768
	ds_read_b128 v[24:27], v156 offset:33792
	ds_read_b128 v[242:245], v156 offset:34816
	ds_read_b128 v[246:249], v156 offset:35840
	ds_read_b128 v[228:231], v156 offset:36864
	ds_read_b128 v[180:183], v156 offset:37888
	ds_read_b128 v[184:187], v156 offset:38912
	ds_read_b128 v[224:227], v156 offset:39936
	global_load_lds_dwordx4 v130, s[2:3]
	s_mov_b32 m0, s47
	s_nop 0
	global_load_lds_dwordx4 v134, s[2:3]
	s_setprio 1
	s_waitcnt vmcnt(8)
	s_waitcnt lgkmcnt(0)
	s_barrier
	s_waitcnt lgkmcnt(0)
	v_mfma_f32_16x16x32_bf16 v[60:63], v[8:11], v[16:19], v[64:67]
	v_mfma_f32_16x16x32_bf16 v[122:125], v[20:23], v[24:27], v[60:63]
	v_mfma_f32_16x16x32_bf16 v[60:63], v[28:31], v[16:19], v[68:71]
	v_mfma_f32_16x16x32_bf16 v[114:117], v[212:215], v[24:27], v[60:63]
	v_mfma_f32_16x16x32_bf16 v[60:63], v[8:11], v[242:245], v[72:75]
	v_mfma_f32_16x16x32_bf16 v[106:109], v[20:23], v[246:249], v[60:63]
	v_mfma_f32_16x16x32_bf16 v[60:63], v[28:31], v[242:245], v[76:79]
	v_mfma_f32_16x16x32_bf16 v[98:101], v[212:215], v[246:249], v[60:63]
	v_mfma_f32_16x16x32_bf16 v[60:63], v[8:11], v[228:231], v[80:83]
	v_mfma_f32_16x16x32_bf16 v[88:91], v[20:23], v[180:183], v[60:63]
	v_mfma_f32_16x16x32_bf16 v[60:63], v[28:31], v[228:231], v[84:87]
	v_mfma_f32_16x16x32_bf16 v[80:83], v[212:215], v[180:183], v[60:63]
	v_mfma_f32_16x16x32_bf16 v[60:63], v[8:11], v[184:187], v[92:95]
	v_mfma_f32_16x16x32_bf16 v[72:75], v[20:23], v[224:227], v[60:63]
	v_mfma_f32_16x16x32_bf16 v[60:63], v[28:31], v[184:187], v[102:105]
	v_mfma_f32_16x16x32_bf16 v[60:63], v[212:215], v[224:227], v[60:63]
	v_mfma_f32_16x16x32_bf16 v[64:67], v[216:219], v[16:19], v[110:113]
	v_mfma_f32_16x16x32_bf16 v[16:19], v[234:237], v[16:19], v[32:35]
	v_mfma_f32_16x16x32_bf16 v[118:121], v[238:241], v[24:27], v[16:19]
	v_mfma_f32_16x16x32_bf16 v[16:19], v[216:219], v[242:245], v[36:39]
	v_mfma_f32_16x16x32_bf16 v[110:113], v[220:223], v[246:249], v[16:19]
	v_mfma_f32_16x16x32_bf16 v[16:19], v[234:237], v[242:245], v[40:43]
	v_mfma_f32_16x16x32_bf16 v[102:105], v[238:241], v[246:249], v[16:19]
	v_mfma_f32_16x16x32_bf16 v[16:19], v[216:219], v[228:231], v[44:47]
	v_mfma_f32_16x16x32_bf16 v[92:95], v[220:223], v[180:183], v[16:19]
	v_mfma_f32_16x16x32_bf16 v[16:19], v[234:237], v[228:231], v[48:51]
	v_mfma_f32_16x16x32_bf16 v[84:87], v[238:241], v[180:183], v[16:19]
	v_mfma_f32_16x16x32_bf16 v[16:19], v[216:219], v[184:187], v[52:55]
	v_mfma_f32_16x16x32_bf16 v[76:79], v[220:223], v[224:227], v[16:19]
	v_mfma_f32_16x16x32_bf16 v[16:19], v[234:237], v[184:187], v[56:59]
	v_mfma_f32_16x16x32_bf16 v[126:129], v[220:223], v[24:27], v[64:67]
	v_mfma_f32_16x16x32_bf16 v[68:71], v[238:241], v[224:227], v[16:19]
	s_barrier
; template <class Epi, class Sched, bool ALIGN_EPI = false, bool SP2 = false>
; __device__ __forceinline__ void gemm_phase(PG8_LAS unsigned char* lds, const Gemm g, const Sched& S, const Epi& E) {
;     ...
;         for (int t = (Epi::PEEL ? 2 : 0); t < nt; t += 2) {
;             const bool last = (t == nt - 2);
;             const char* a1 = cA + (size_t)(t + 1) * kstepA;
;             const char* a2 = last ? nA : cA + (size_t)(t + 2) * kstepA; const char* b2 = last ? nB : cB + (size_t)(t + 2) * kstepB;
;             const char* a3 = a2 + kstepA; const char* b3 = b2 + kstepB;
;             PG8_ITER(8);
	s_setprio 0
	s_mov_b64 s[2:3], 0x180
	s_add_i32 s99, s99, s9
	s_nop 1
	v_lshl_add_u64 v[16:17], v[154:155], 0, s[2:3]
	s_mov_b32 m0, s99
	s_add_i32 vcc_lo, s99, 0x2000
	ds_read_b128 v[36:39], v156 offset:49152
	ds_read_b128 v[44:47], v156 offset:50176
	ds_read_b128 v[180:183], v156 offset:51200
	ds_read_b128 v[184:187], v156 offset:52224
	ds_read_b128 v[224:227], v156 offset:53248
	ds_read_b128 v[228:231], v156 offset:54272
	ds_read_b128 v[242:245], v156 offset:55296
	ds_read_b128 v[246:249], v156 offset:56320
	global_load_lds_dwordx4 v[16:17], off
	v_lshl_add_u64 v[16:17], v[178:179], 0, s[2:3]
	s_add_u32 s2, s0, 0x40180
	s_mov_b32 m0, vcc_lo
	s_addc_u32 s3, s1, 0
	s_add_i32 vcc_hi, vcc_hi, s9
	global_load_lds_dwordx4 v[16:17], off
	s_mov_b32 m0, vcc_hi
	s_add_i32 s38, vcc_hi, 0x2000
	global_load_lds_dwordx4 v132, s[2:3]
	s_mov_b32 m0, s38
	s_nop 0
	global_load_lds_dwordx4 v136, s[2:3]
	s_mov_b32 m0, s49
	s_nop 0
	global_load_lds_dwordx4 v130, s[42:43]
	s_mov_b32 m0, s50
	s_nop 0
	global_load_lds_dwordx4 v134, s[42:43]
	s_setprio 1
	s_waitcnt vmcnt(8)
	s_waitcnt lgkmcnt(0)
	s_barrier
	s_waitcnt lgkmcnt(0)
	v_mfma_f32_16x16x32_bf16 v[16:19], v[8:11], v[36:39], v[146:149]
	v_mfma_f32_16x16x32_bf16 v[56:59], v[20:23], v[44:47], v[16:19]
	v_mfma_f32_16x16x32_bf16 v[16:19], v[28:31], v[36:39], v[150:153]
	v_mfma_f32_16x16x32_bf16 v[48:51], v[212:215], v[44:47], v[16:19]
	v_mfma_f32_16x16x32_bf16 v[16:19], v[8:11], v[180:183], v[158:161]
	v_mfma_f32_16x16x32_bf16 v[40:43], v[20:23], v[184:187], v[16:19]
	v_mfma_f32_16x16x32_bf16 v[16:19], v[28:31], v[180:183], v[162:165]
	v_mfma_f32_16x16x32_bf16 v[32:35], v[212:215], v[184:187], v[16:19]
	v_mfma_f32_16x16x32_bf16 v[16:19], v[8:11], v[224:227], v[166:169]
	v_mfma_f32_16x16x32_bf16 v[0:3], v[8:11], v[242:245], v[0:3]
	v_mfma_f32_16x16x32_bf16 v[24:27], v[20:23], v[228:231], v[16:19]
	v_mfma_f32_16x16x32_bf16 v[16:19], v[28:31], v[224:227], v[170:173]
	v_mfma_f32_16x16x32_bf16 v[8:11], v[20:23], v[246:249], v[0:3]
	v_mfma_f32_16x16x32_bf16 v[0:3], v[28:31], v[242:245], v[4:7]
	v_mfma_f32_16x16x32_bf16 v[16:19], v[212:215], v[228:231], v[16:19]
	v_mfma_f32_16x16x32_bf16 v[0:3], v[212:215], v[246:249], v[0:3]
	v_mfma_f32_16x16x32_bf16 v[4:7], v[216:219], v[36:39], v[12:15]
	v_mfma_f32_16x16x32_bf16 v[64:67], v[220:223], v[44:47], v[4:7]
	v_mfma_f32_16x16x32_bf16 v[4:7], v[234:237], v[36:39], v[174:177]
	v_mfma_f32_16x16x32_bf16 v[52:55], v[238:241], v[44:47], v[4:7]
	v_mfma_f32_16x16x32_bf16 v[4:7], v[216:219], v[180:183], v[188:191]
	v_mfma_f32_16x16x32_bf16 v[44:47], v[220:223], v[184:187], v[4:7]
	v_mfma_f32_16x16x32_bf16 v[4:7], v[234:237], v[180:183], v[192:195]
	v_mfma_f32_16x16x32_bf16 v[36:39], v[238:241], v[184:187], v[4:7]
	v_mfma_f32_16x16x32_bf16 v[4:7], v[216:219], v[224:227], v[196:199]
	v_mfma_f32_16x16x32_bf16 v[28:31], v[220:223], v[228:231], v[4:7]
	v_mfma_f32_16x16x32_bf16 v[4:7], v[234:237], v[224:227], v[200:203]
	v_mfma_f32_16x16x32_bf16 v[20:23], v[238:241], v[228:231], v[4:7]
	v_mfma_f32_16x16x32_bf16 v[4:7], v[216:219], v[242:245], v[204:207]
	v_mfma_f32_16x16x32_bf16 v[12:15], v[220:223], v[246:249], v[4:7]
	v_mfma_f32_16x16x32_bf16 v[4:7], v[234:237], v[242:245], v[208:211]
	v_mfma_f32_16x16x32_bf16 v[4:7], v[238:241], v[246:249], v[4:7]
	s_barrier
	s_setprio 0
	s_add_u32 s3, s0, 0x200
	s_addc_u32 s2, s1, 0
	s_add_u32 s0, s34, 0xc04000
	s_addc_u32 s1, s35, 0
	s_mov_b32 s18, 0
.LBB0_478:
	ds_read_b128 v[146:149], v142
	ds_read_b128 v[150:153], v142 offset:1024
	ds_read_b128 v[158:161], v142 offset:2048
	ds_read_b128 v[162:165], v142 offset:3072
	ds_read_b128 v[166:169], v143
	ds_read_b128 v[170:173], v143 offset:1024
	ds_read_b128 v[174:177], v143 offset:2048
	ds_read_b128 v[180:183], v143 offset:3072
	s_add_u32 s10, s0, 0x3fc000
	s_addc_u32 s11, s1, 0
	s_cmp_eq_u32 s18, 12
	s_cselect_b32 s44, s27, s10
	s_cselect_b32 s45, s25, s11
	s_cselect_b32 s42, s58, s3
	s_cselect_b32 s43, s57, s2
	s_add_u32 s34, s44, 0x400000
	s_addc_u32 s35, s45, 0
	s_mov_b32 m0, s59
	ds_read_b128 v[184:187], v156
	ds_read_b128 v[188:191], v156 offset:1024
	ds_read_b128 v[192:195], v156 offset:2048
	ds_read_b128 v[196:199], v156 offset:3072
	ds_read_b128 v[200:203], v156 offset:4096
	ds_read_b128 v[204:207], v156 offset:5120
	ds_read_b128 v[208:211], v156 offset:6144
	ds_read_b128 v[212:215], v156 offset:7168
	global_load_lds_dwordx4 v140, s[0:1]
	s_mov_b32 m0, s60
	s_nop 0
	global_load_lds_dwordx4 v138, s[0:1]
	s_setprio 1
	s_waitcnt vmcnt(8)
	s_waitcnt lgkmcnt(0)
	s_barrier
	s_waitcnt lgkmcnt(0)
	v_mfma_f32_16x16x32_bf16 v[122:125], v[146:149], v[184:187], v[122:125]
	v_mfma_f32_16x16x32_bf16 v[114:117], v[158:161], v[184:187], v[114:117]
	v_mfma_f32_16x16x32_bf16 v[98:101], v[158:161], v[192:195], v[98:101]
	v_mfma_f32_16x16x32_bf16 v[106:109], v[146:149], v[192:195], v[106:109]
	v_mfma_f32_16x16x32_bf16 v[88:91], v[146:149], v[200:203], v[88:91]
	v_mfma_f32_16x16x32_bf16 v[80:83], v[158:161], v[200:203], v[80:83]
	v_mfma_f32_16x16x32_bf16 v[60:63], v[158:161], v[208:211], v[60:63]
	v_mfma_f32_16x16x32_bf16 v[72:75], v[146:149], v[208:211], v[72:75]
	v_mfma_f32_16x16x32_bf16 v[122:125], v[150:153], v[188:191], v[122:125]
	v_mfma_f32_16x16x32_bf16 v[114:117], v[162:165], v[188:191], v[114:117]
	v_mfma_f32_16x16x32_bf16 v[98:101], v[162:165], v[196:199], v[98:101]
	v_mfma_f32_16x16x32_bf16 v[106:109], v[150:153], v[196:199], v[106:109]
	v_mfma_f32_16x16x32_bf16 v[88:91], v[150:153], v[204:207], v[88:91]
	v_mfma_f32_16x16x32_bf16 v[80:83], v[162:165], v[204:207], v[80:83]
	v_mfma_f32_16x16x32_bf16 v[60:63], v[162:165], v[212:215], v[60:63]
	v_mfma_f32_16x16x32_bf16 v[72:75], v[150:153], v[212:215], v[72:75]
	v_mfma_f32_16x16x32_bf16 v[126:129], v[166:169], v[184:187], v[126:129]
	v_mfma_f32_16x16x32_bf16 v[118:121], v[174:177], v[184:187], v[118:121]
	v_mfma_f32_16x16x32_bf16 v[102:105], v[174:177], v[192:195], v[102:105]
	v_mfma_f32_16x16x32_bf16 v[110:113], v[166:169], v[192:195], v[110:113]
	v_mfma_f32_16x16x32_bf16 v[92:95], v[166:169], v[200:203], v[92:95]
	v_mfma_f32_16x16x32_bf16 v[84:87], v[174:177], v[200:203], v[84:87]
	v_mfma_f32_16x16x32_bf16 v[68:71], v[174:177], v[208:211], v[68:71]
	v_mfma_f32_16x16x32_bf16 v[76:79], v[166:169], v[208:211], v[76:79]
	v_mfma_f32_16x16x32_bf16 v[126:129], v[170:173], v[188:191], v[126:129]
	v_mfma_f32_16x16x32_bf16 v[118:121], v[180:183], v[188:191], v[118:121]
	v_mfma_f32_16x16x32_bf16 v[102:105], v[180:183], v[196:199], v[102:105]
	v_mfma_f32_16x16x32_bf16 v[110:113], v[170:173], v[196:199], v[110:113]
	v_mfma_f32_16x16x32_bf16 v[92:95], v[170:173], v[204:207], v[92:95]
	v_mfma_f32_16x16x32_bf16 v[84:87], v[180:183], v[204:207], v[84:87]
	v_mfma_f32_16x16x32_bf16 v[68:71], v[180:183], v[212:215], v[68:71]
	v_mfma_f32_16x16x32_bf16 v[76:79], v[170:173], v[212:215], v[76:79]
	s_barrier
	s_setprio 0
	s_mov_b32 m0, s61
	s_add_u32 s10, s42, 0x40000
	ds_read_b128 v[184:187], v156 offset:16384
	ds_read_b128 v[188:191], v156 offset:17408
	ds_read_b128 v[192:195], v156 offset:18432
	ds_read_b128 v[196:199], v156 offset:19456
	ds_read_b128 v[200:203], v156 offset:20480
	ds_read_b128 v[204:207], v156 offset:21504
	ds_read_b128 v[208:211], v156 offset:22528
	ds_read_b128 v[212:215], v156 offset:23552
	global_load_lds_dwordx4 v132, s[42:43]
	s_mov_b32 m0, s96
	s_addc_u32 s11, s43, 0
	global_load_lds_dwordx4 v136, s[42:43]
	s_mov_b32 m0, s97
	s_nop 0
	global_load_lds_dwordx4 v132, s[10:11]
	s_mov_b32 m0, s98
	s_nop 0
	global_load_lds_dwordx4 v136, s[10:11]
	s_mov_b32 m0, s23
	s_nop 0
	global_load_lds_dwordx4 v130, s[44:45]
	s_mov_b32 m0, s39
	s_nop 0
	global_load_lds_dwordx4 v134, s[44:45]
	s_setprio 1
	s_waitcnt vmcnt(8)
	s_waitcnt lgkmcnt(0)
	s_barrier
	s_waitcnt lgkmcnt(0)
	v_mfma_f32_16x16x32_bf16 v[56:59], v[146:149], v[184:187], v[56:59]
	v_mfma_f32_16x16x32_bf16 v[48:51], v[158:161], v[184:187], v[48:51]
	v_mfma_f32_16x16x32_bf16 v[32:35], v[158:161], v[192:195], v[32:35]
	v_mfma_f32_16x16x32_bf16 v[40:43], v[146:149], v[192:195], v[40:43]
	v_mfma_f32_16x16x32_bf16 v[24:27], v[146:149], v[200:203], v[24:27]
	v_mfma_f32_16x16x32_bf16 v[16:19], v[158:161], v[200:203], v[16:19]
	v_mfma_f32_16x16x32_bf16 v[0:3], v[158:161], v[208:211], v[0:3]
	v_mfma_f32_16x16x32_bf16 v[8:11], v[146:149], v[208:211], v[8:11]
	v_mfma_f32_16x16x32_bf16 v[56:59], v[150:153], v[188:191], v[56:59]
	v_mfma_f32_16x16x32_bf16 v[48:51], v[162:165], v[188:191], v[48:51]
	v_mfma_f32_16x16x32_bf16 v[32:35], v[162:165], v[196:199], v[32:35]
	v_mfma_f32_16x16x32_bf16 v[40:43], v[150:153], v[196:199], v[40:43]
	v_mfma_f32_16x16x32_bf16 v[24:27], v[150:153], v[204:207], v[24:27]
	v_mfma_f32_16x16x32_bf16 v[16:19], v[162:165], v[204:207], v[16:19]
	v_mfma_f32_16x16x32_bf16 v[0:3], v[162:165], v[212:215], v[0:3]
	v_mfma_f32_16x16x32_bf16 v[8:11], v[150:153], v[212:215], v[8:11]
	v_mfma_f32_16x16x32_bf16 v[64:67], v[166:169], v[184:187], v[64:67]
	v_mfma_f32_16x16x32_bf16 v[52:55], v[174:177], v[184:187], v[52:55]
	v_mfma_f32_16x16x32_bf16 v[36:39], v[174:177], v[192:195], v[36:39]
	v_mfma_f32_16x16x32_bf16 v[44:47], v[166:169], v[192:195], v[44:47]
	v_mfma_f32_16x16x32_bf16 v[28:31], v[166:169], v[200:203], v[28:31]
	v_mfma_f32_16x16x32_bf16 v[20:23], v[174:177], v[200:203], v[20:23]
	v_mfma_f32_16x16x32_bf16 v[4:7], v[174:177], v[208:211], v[4:7]
	v_mfma_f32_16x16x32_bf16 v[12:15], v[166:169], v[208:211], v[12:15]
	v_mfma_f32_16x16x32_bf16 v[64:67], v[170:173], v[188:191], v[64:67]
	v_mfma_f32_16x16x32_bf16 v[52:55], v[180:183], v[188:191], v[52:55]
	v_mfma_f32_16x16x32_bf16 v[36:39], v[180:183], v[196:199], v[36:39]
	v_mfma_f32_16x16x32_bf16 v[44:47], v[170:173], v[196:199], v[44:47]
	v_mfma_f32_16x16x32_bf16 v[28:31], v[170:173], v[204:207], v[28:31]
	v_mfma_f32_16x16x32_bf16 v[20:23], v[180:183], v[204:207], v[20:23]
	v_mfma_f32_16x16x32_bf16 v[4:7], v[180:183], v[212:215], v[4:7]
	v_mfma_f32_16x16x32_bf16 v[12:15], v[170:173], v[212:215], v[12:15]
	s_barrier
; #define PG8_BAR __builtin_amdgcn_s_barrier()
; template <class Epi, class Sched, bool ALIGN_EPI = false, bool SP2 = false>
; __device__ __forceinline__ void gemm_phase(PG8_LAS unsigned char* lds, const Gemm g, const Sched& S, const Epi& E) {
;     ...
;         for (int t = (Epi::PEEL ? 2 : 0); t < nt; t += 2) {
;             const bool last = (t == nt - 2);
;             const char* a1 = cA + (size_t)(t + 1) * kstepA;
;             const char* a2 = last ? nA : cA + (size_t)(t + 2) * kstepA; const char* b2 = last ? nB : cB + (size_t)(t + 2) * kstepB;
;             const char* a3 = a2 + kstepA; const char* b3 = b2 + kstepB;
;             PG8_ITER(8);
;         }
;     ...
;         if constexpr (ALIGN_EPI) { if (wr == 0) PG8_BAR; }
	s_setprio 0
	ds_read_b128 v[146:149], v144
	ds_read_b128 v[150:153], v144 offset:1024
	ds_read_b128 v[158:161], v144 offset:2048
	ds_read_b128 v[162:165], v144 offset:3072
	ds_read_b128 v[166:169], v145
	ds_read_b128 v[170:173], v145 offset:1024
	ds_read_b128 v[174:177], v145 offset:2048
	ds_read_b128 v[180:183], v145 offset:3072
	s_add_u32 s10, s44, 0x4000
	s_addc_u32 s11, s45, 0
	s_mov_b32 m0, s46
	ds_read_b128 v[184:187], v156 offset:32768
	ds_read_b128 v[188:191], v156 offset:33792
	ds_read_b128 v[192:195], v156 offset:34816
	ds_read_b128 v[196:199], v156 offset:35840
	ds_read_b128 v[200:203], v156 offset:36864
	ds_read_b128 v[204:207], v156 offset:37888
	ds_read_b128 v[208:211], v156 offset:38912
	ds_read_b128 v[212:215], v156 offset:39936
	global_load_lds_dwordx4 v130, s[10:11]
	s_mov_b32 m0, s47
	s_nop 0
	global_load_lds_dwordx4 v134, s[10:11]
	s_setprio 1
	s_waitcnt vmcnt(8)
	s_waitcnt lgkmcnt(0)
	s_barrier
	s_waitcnt lgkmcnt(0)
	v_mfma_f32_16x16x32_bf16 v[122:125], v[146:149], v[184:187], v[122:125]
	v_mfma_f32_16x16x32_bf16 v[114:117], v[158:161], v[184:187], v[114:117]
	v_mfma_f32_16x16x32_bf16 v[98:101], v[158:161], v[192:195], v[98:101]
	v_mfma_f32_16x16x32_bf16 v[106:109], v[146:149], v[192:195], v[106:109]
	v_mfma_f32_16x16x32_bf16 v[88:91], v[146:149], v[200:203], v[88:91]
	v_mfma_f32_16x16x32_bf16 v[80:83], v[158:161], v[200:203], v[80:83]
	v_mfma_f32_16x16x32_bf16 v[60:63], v[158:161], v[208:211], v[60:63]
	v_mfma_f32_16x16x32_bf16 v[72:75], v[146:149], v[208:211], v[72:75]
	v_mfma_f32_16x16x32_bf16 v[122:125], v[150:153], v[188:191], v[122:125]
	v_mfma_f32_16x16x32_bf16 v[114:117], v[162:165], v[188:191], v[114:117]
	v_mfma_f32_16x16x32_bf16 v[98:101], v[162:165], v[196:199], v[98:101]
	v_mfma_f32_16x16x32_bf16 v[106:109], v[150:153], v[196:199], v[106:109]
	v_mfma_f32_16x16x32_bf16 v[88:91], v[150:153], v[204:207], v[88:91]
	v_mfma_f32_16x16x32_bf16 v[80:83], v[162:165], v[204:207], v[80:83]
	v_mfma_f32_16x16x32_bf16 v[60:63], v[162:165], v[212:215], v[60:63]
	v_mfma_f32_16x16x32_bf16 v[72:75], v[150:153], v[212:215], v[72:75]
	v_mfma_f32_16x16x32_bf16 v[126:129], v[166:169], v[184:187], v[126:129]
	v_mfma_f32_16x16x32_bf16 v[118:121], v[174:177], v[184:187], v[118:121]
	v_mfma_f32_16x16x32_bf16 v[102:105], v[174:177], v[192:195], v[102:105]
	v_mfma_f32_16x16x32_bf16 v[110:113], v[166:169], v[192:195], v[110:113]
	v_mfma_f32_16x16x32_bf16 v[92:95], v[166:169], v[200:203], v[92:95]
	v_mfma_f32_16x16x32_bf16 v[84:87], v[174:177], v[200:203], v[84:87]
	v_mfma_f32_16x16x32_bf16 v[68:71], v[174:177], v[208:211], v[68:71]
	v_mfma_f32_16x16x32_bf16 v[76:79], v[166:169], v[208:211], v[76:79]
	v_mfma_f32_16x16x32_bf16 v[126:129], v[170:173], v[188:191], v[126:129]
	v_mfma_f32_16x16x32_bf16 v[118:121], v[180:183], v[188:191], v[118:121]
	v_mfma_f32_16x16x32_bf16 v[102:105], v[180:183], v[196:199], v[102:105]
	v_mfma_f32_16x16x32_bf16 v[110:113], v[170:173], v[196:199], v[110:113]
	v_mfma_f32_16x16x32_bf16 v[92:95], v[170:173], v[204:207], v[92:95]
	v_mfma_f32_16x16x32_bf16 v[84:87], v[180:183], v[204:207], v[84:87]
	v_mfma_f32_16x16x32_bf16 v[68:71], v[180:183], v[212:215], v[68:71]
	v_mfma_f32_16x16x32_bf16 v[76:79], v[170:173], v[212:215], v[76:79]
	s_barrier
	s_setprio 0
	s_mov_b32 m0, s99
	s_add_u32 s100, s42, 0x80
	s_addc_u32 s101, s43, 0
	s_add_u32 s10, s42, 0x40080
	ds_read_b128 v[184:187], v156 offset:49152
	ds_read_b128 v[188:191], v156 offset:50176
	ds_read_b128 v[192:195], v156 offset:51200
	ds_read_b128 v[196:199], v156 offset:52224
	ds_read_b128 v[200:203], v156 offset:53248
	ds_read_b128 v[204:207], v156 offset:54272
	ds_read_b128 v[208:211], v156 offset:55296
	ds_read_b128 v[212:215], v156 offset:56320
	global_load_lds_dwordx4 v132, s[100:101]
	s_mov_b32 m0, vcc_lo
	s_addc_u32 s11, s43, 0
	global_load_lds_dwordx4 v136, s[100:101]
	s_mov_b32 m0, vcc_hi
	s_nop 0
	global_load_lds_dwordx4 v132, s[10:11]
	s_mov_b32 m0, s38
	s_nop 0
	global_load_lds_dwordx4 v136, s[10:11]
	s_mov_b32 m0, s49
	s_nop 0
	global_load_lds_dwordx4 v130, s[34:35]
	s_mov_b32 m0, s50
	s_nop 0
	global_load_lds_dwordx4 v134, s[34:35]
	s_setprio 1
	s_waitcnt vmcnt(8)
	s_waitcnt lgkmcnt(0)
	s_barrier
	s_waitcnt lgkmcnt(0)
	v_mfma_f32_16x16x32_bf16 v[56:59], v[146:149], v[184:187], v[56:59]
	v_mfma_f32_16x16x32_bf16 v[48:51], v[158:161], v[184:187], v[48:51]
	v_mfma_f32_16x16x32_bf16 v[32:35], v[158:161], v[192:195], v[32:35]
	v_mfma_f32_16x16x32_bf16 v[40:43], v[146:149], v[192:195], v[40:43]
	v_mfma_f32_16x16x32_bf16 v[24:27], v[146:149], v[200:203], v[24:27]
	v_mfma_f32_16x16x32_bf16 v[16:19], v[158:161], v[200:203], v[16:19]
	v_mfma_f32_16x16x32_bf16 v[0:3], v[158:161], v[208:211], v[0:3]
	v_mfma_f32_16x16x32_bf16 v[8:11], v[146:149], v[208:211], v[8:11]
	v_mfma_f32_16x16x32_bf16 v[56:59], v[150:153], v[188:191], v[56:59]
	v_mfma_f32_16x16x32_bf16 v[48:51], v[162:165], v[188:191], v[48:51]
	v_mfma_f32_16x16x32_bf16 v[32:35], v[162:165], v[196:199], v[32:35]
	v_mfma_f32_16x16x32_bf16 v[40:43], v[150:153], v[196:199], v[40:43]
	v_mfma_f32_16x16x32_bf16 v[24:27], v[150:153], v[204:207], v[24:27]
	v_mfma_f32_16x16x32_bf16 v[16:19], v[162:165], v[204:207], v[16:19]
	v_mfma_f32_16x16x32_bf16 v[0:3], v[162:165], v[212:215], v[0:3]
	v_mfma_f32_16x16x32_bf16 v[8:11], v[150:153], v[212:215], v[8:11]
	v_mfma_f32_16x16x32_bf16 v[64:67], v[166:169], v[184:187], v[64:67]
	v_mfma_f32_16x16x32_bf16 v[52:55], v[174:177], v[184:187], v[52:55]
	v_mfma_f32_16x16x32_bf16 v[36:39], v[174:177], v[192:195], v[36:39]
	v_mfma_f32_16x16x32_bf16 v[44:47], v[166:169], v[192:195], v[44:47]
	v_mfma_f32_16x16x32_bf16 v[28:31], v[166:169], v[200:203], v[28:31]
	v_mfma_f32_16x16x32_bf16 v[20:23], v[174:177], v[200:203], v[20:23]
	v_mfma_f32_16x16x32_bf16 v[4:7], v[174:177], v[208:211], v[4:7]
	v_mfma_f32_16x16x32_bf16 v[12:15], v[166:169], v[208:211], v[12:15]
	v_mfma_f32_16x16x32_bf16 v[64:67], v[170:173], v[188:191], v[64:67]
	v_mfma_f32_16x16x32_bf16 v[52:55], v[180:183], v[188:191], v[52:55]
	v_mfma_f32_16x16x32_bf16 v[36:39], v[180:183], v[196:199], v[36:39]
	v_mfma_f32_16x16x32_bf16 v[44:47], v[170:173], v[196:199], v[44:47]
	v_mfma_f32_16x16x32_bf16 v[28:31], v[170:173], v[204:207], v[28:31]
	v_mfma_f32_16x16x32_bf16 v[20:23], v[180:183], v[204:207], v[20:23]
	v_mfma_f32_16x16x32_bf16 v[4:7], v[180:183], v[212:215], v[4:7]
	v_mfma_f32_16x16x32_bf16 v[12:15], v[170:173], v[212:215], v[12:15]
	s_barrier
	s_setprio 0
	s_add_i32 s18, s18, 2
	s_add_u32 s3, s3, 0x100
	s_addc_u32 s2, s2, 0
	s_add_u32 s0, s0, 0x800000
	s_addc_u32 s1, s1, 0
	s_cmp_gt_u32 s18, 13
	s_cbranch_scc0 .LBB0_478
	s_and_b64 vcc, exec, s[16:17]
	s_cbranch_vccz .LBB0_481
	s_barrier
